# attention fast body now covers the diagonal step with generated masks and issues the KV prefetch under the first LDS reads
# speedup vs baseline: 1.0290x; 1.0013x over previous
; #define ATT_LOADG(t) do { kA = *(const u32x4*)(Kh + (size_t)(t) * 6144 + tid * 8); if (tid < 256) kB = *(const u32x4*)(Kh + (size_t)(t) * 6144 + c2 * 8); \
;         vA = *(const u32x4*)(Vh + (size_t)vr * T + 64 * (t) + vc * 8); } while (0)
; #define ATT_LOADG(t) do { kA = *(const u32x4*)(Kh + (size_t)(t) * 6144 + tid * 8); if (tid < 256) kB = *(const u32x4*)(Kh + (size_t)(t) * 6144 + c2 * 8); \
;         vA = *(const u32x4*)(Vh + (size_t)vr * T + 64 * (t) + vc * 8); } while (0)
; __device__ __forceinline__ void attn_unit64(const bf16_t* Q, const bf16_t* K, const bf16_t* Vt, bf16_t* O, int bh, int qb8, float mfix, LAS unsigned char* lds) {
;     ...
;     for (int t = 0; t < NTL; ++t) {
;         const int buf = t & 1;
;         if (t + 1 < NTL) ATT_LOADG(t + 1);
;         if (t <= tmaxw) {
.LBB0_793:
	s_cmp_le_u32 s33, s24
	s_cbranch_scc1 .Lattn_fast_1
	s_add_i32 s28, s33, 1
	s_cmp_lt_u32 s28, s25
	s_cselect_b64 s[20:21], -1, 0
	s_cmp_ge_u32 s28, s25
	s_cbranch_scc1 .LBB0_798
	global_load_dwordx4 v[112:115], v[130:131], off
	s_and_saveexec_b64 s[4:5], s[0:1]
	s_cbranch_execz .LBB0_796
	v_add_co_u32_e32 v80, vcc, 0x2000, v130
	s_nop 1
	v_addc_co_u32_e32 v81, vcc, 0, v131, vcc
	global_load_dwordx4 v[116:119], v[80:81], off

; #define LAS __attribute__((address_space(3)))
; #define MFMA32(a, b, c) __builtin_amdgcn_mfma_f32_32x32x16_bf16((a), (b), (c), 0, 0, 0)
; #define ATT_LOADG(t) do { kA = *(const u32x4*)(Kh + (size_t)(t) * 6144 + tid * 8); if (tid < 256) kB = *(const u32x4*)(Kh + (size_t)(t) * 6144 + c2 * 8); \
;         vA = *(const u32x4*)(Vh + (size_t)vr * T + 64 * (t) + vc * 8); } while (0)
; #define ATT_LOADG(t) do { kA = *(const u32x4*)(Kh + (size_t)(t) * 6144 + tid * 8); if (tid < 256) kB = *(const u32x4*)(Kh + (size_t)(t) * 6144 + c2 * 8); \
;         vA = *(const u32x4*)(Vh + (size_t)vr * T + 64 * (t) + vc * 8); } while (0)
; __device__ __forceinline__ void attn_unit64(const bf16_t* Q, const bf16_t* K, const bf16_t* Vt, bf16_t* O, int bh, int qb8, float mfix, LAS unsigned char* lds) {
;     ...
;         const int buf = t & 1;
;         if (t + 1 < NTL) ATT_LOADG(t + 1);
;         if (t <= tmaxw) {
;             const LAS bf16_t* kp = Kb + buf * 6656 + r * 104 + 8 * hh;
;             const LAS bf16_t* vp = Vb + buf * 4352 + r * 68 + 4 * hh;
; #pragma unroll
;             for (int half = 0; half < 2; ++half) {
;                 f32x16 sA, sB;
; #pragma unroll
;                 for (int i = 0; i < 16; ++i) { sA[i] = -mfix; sB[i] = -mfix; }
; #pragma unroll
;                 for (int d0 = 0; d0 < 6; ++d0) { const bf16x8 a = *(const LAS bf16x8*)(kp + half * 32 * 104 + 16 * d0); const bf16x8 qa_ = Qs[512 * d0], qb_ = Qs[512 * (6 + d0)]; sA = MFMA32(a, qa_, sA); sB = MFMA32(a, qb_, sB); }
.Lattn_fast_1:
	s_add_i32 s28, s33, 1
	s_cmp_lt_u32 s28, s25
	s_cselect_b64 s[20:21], -1, 0
	s_and_b32 s29, s33, 1
	s_cmp_eq_u32 s33, s24
	s_cbranch_scc1 .Lattn_fastd_1
	s_mul_i32 s4, s29, 0x3400
	v_add_u32_e32 v180, s4, v188
	s_mul_i32 s4, s29, 0x2200
	v_add_u32_e32 v177, s4, v198
	v_add_u32_e32 v178, 0x6800, v177
	ds_read_b128 v[248:251], v180
	ds_read_b128 v[158:161], v180 offset:32
	s_cmp_lg_u64 s[20:21], 0
	s_cbranch_scc0 .Lattn_nold_1n
	global_load_dwordx4 v[112:115], v[130:131], off
	s_and_saveexec_b64 s[4:5], s[0:1]
	v_add_co_u32_e32 v252, vcc, 0x2000, v130
	s_nop 1
	v_addc_co_u32_e32 v253, vcc, 0, v131, vcc
	global_load_dwordx4 v[116:119], v[252:253], off
	s_or_b64 exec, exec, s[4:5]
	global_load_dwordx4 v[120:123], v[128:129], off
.Lattn_nold_1n:
	s_nop 3
	s_setprio 1
	s_waitcnt lgkmcnt(1)
	v_mfma_f32_32x32x16_bf16 v[96:111], v[248:251], v[132:135], v[0:15]
	v_mfma_f32_32x32x16_bf16 v[80:95], v[248:251], v[214:217], v[0:15]
	ds_read_b128 v[248:251], v180 offset:64
	s_waitcnt lgkmcnt(1)
	v_mfma_f32_32x32x16_bf16 v[96:111], v[158:161], v[136:139], v[96:111]
	v_mfma_f32_32x32x16_bf16 v[80:95], v[158:161], v[218:221], v[80:95]
	ds_read_b128 v[158:161], v180 offset:96
	s_waitcnt lgkmcnt(1)
	v_mfma_f32_32x32x16_bf16 v[96:111], v[248:251], v[140:143], v[96:111]
	v_mfma_f32_32x32x16_bf16 v[80:95], v[248:251], v[232:235], v[80:95]
	ds_read_b128 v[248:251], v180 offset:128
	s_waitcnt lgkmcnt(1)
	v_mfma_f32_32x32x16_bf16 v[96:111], v[158:161], v[144:147], v[96:111]
	v_mfma_f32_32x32x16_bf16 v[80:95], v[158:161], v[236:239], v[80:95]
	ds_read_b128 v[158:161], v180 offset:160
	s_waitcnt lgkmcnt(1)
	v_mfma_f32_32x32x16_bf16 v[96:111], v[248:251], v[206:209], v[96:111]
	v_mfma_f32_32x32x16_bf16 v[80:95], v[248:251], v[240:243], v[80:95]
	s_waitcnt lgkmcnt(0)
	v_mfma_f32_32x32x16_bf16 v[96:111], v[158:161], v[210:213], v[96:111]
	v_mfma_f32_32x32x16_bf16 v[80:95], v[158:161], v[244:247], v[80:95]
	ds_read_b64 v[248:249], v178 offset:0
	ds_read_b64 v[250:251], v178 offset:16
	ds_read_b64 v[158:159], v178 offset:4352
	ds_read_b64 v[160:161], v178 offset:4368
	s_setprio 0
	s_nop 5
	v_exp_f32_e32 v96, v96
	v_exp_f32_e32 v97, v97
	v_exp_f32_e32 v98, v98
	v_exp_f32_e32 v99, v99
	v_add_f32_e32 v182, v96, v97
	v_cvt_pk_bf16_f32 v96, v96, v97
	v_exp_f32_e32 v100, v100
	v_exp_f32_e32 v101, v101
	v_add_f32_e32 v182, v182, v98
	v_add_f32_e32 v182, v182, v99
	v_cvt_pk_bf16_f32 v97, v98, v99
	v_exp_f32_e32 v102, v102
	v_exp_f32_e32 v103, v103
	v_add_f32_e32 v182, v182, v100
	v_add_f32_e32 v182, v182, v101
	v_cvt_pk_bf16_f32 v98, v100, v101
	v_exp_f32_e32 v80, v80
	v_exp_f32_e32 v81, v81
	v_add_f32_e32 v182, v182, v102
	v_add_f32_e32 v182, v182, v103
	v_cvt_pk_bf16_f32 v99, v102, v103
	v_exp_f32_e32 v82, v82
	v_exp_f32_e32 v83, v83
	v_add_f32_e32 v162, v80, v81
	v_cvt_pk_bf16_f32 v80, v80, v81
	v_exp_f32_e32 v84, v84
	v_exp_f32_e32 v85, v85
	v_add_f32_e32 v162, v162, v82
	v_add_f32_e32 v162, v162, v83
	v_cvt_pk_bf16_f32 v81, v82, v83
	v_exp_f32_e32 v86, v86
	v_exp_f32_e32 v87, v87
	v_add_f32_e32 v162, v162, v84
	v_add_f32_e32 v162, v162, v85
	v_cvt_pk_bf16_f32 v82, v84, v85
	v_exp_f32_e32 v104, v104
	v_exp_f32_e32 v105, v105
	v_add_f32_e32 v162, v162, v86
	v_add_f32_e32 v162, v162, v87
	v_cvt_pk_bf16_f32 v83, v86, v87
	v_exp_f32_e32 v106, v106
	v_exp_f32_e32 v107, v107
	v_add_f32_e32 v182, v182, v104
	v_add_f32_e32 v182, v182, v105
	v_cvt_pk_bf16_f32 v100, v104, v105
	v_exp_f32_e32 v108, v108
	v_exp_f32_e32 v109, v109
	v_add_f32_e32 v182, v182, v106
	v_add_f32_e32 v182, v182, v107
	v_cvt_pk_bf16_f32 v101, v106, v107
	v_exp_f32_e32 v110, v110
	v_exp_f32_e32 v111, v111
	v_add_f32_e32 v182, v182, v108
	v_add_f32_e32 v182, v182, v109
	v_cvt_pk_bf16_f32 v102, v108, v109
	v_exp_f32_e32 v88, v88
	v_exp_f32_e32 v89, v89
	v_add_f32_e32 v182, v182, v110
	v_add_f32_e32 v182, v182, v111
	v_cvt_pk_bf16_f32 v103, v110, v111
	ds_read_b64 v[104:105], v178 offset:32
	ds_read_b64 v[106:107], v178 offset:48
	ds_read_b64 v[108:109], v178 offset:4384
	ds_read_b64 v[110:111], v178 offset:4400
	v_exp_f32_e32 v90, v90
	v_exp_f32_e32 v91, v91
	v_add_f32_e32 v162, v162, v88
	v_add_f32_e32 v162, v162, v89
	v_cvt_pk_bf16_f32 v84, v88, v89
	v_exp_f32_e32 v92, v92
	v_exp_f32_e32 v93, v93
	v_add_f32_e32 v162, v162, v90
	v_add_f32_e32 v162, v162, v91
	v_cvt_pk_bf16_f32 v85, v90, v91
	v_exp_f32_e32 v94, v94
	v_exp_f32_e32 v95, v95
	v_add_f32_e32 v162, v162, v92
	v_add_f32_e32 v162, v162, v93
	v_cvt_pk_bf16_f32 v86, v92, v93
	v_add_f32_e32 v162, v162, v94
	v_add_f32_e32 v162, v162, v95
	v_cvt_pk_bf16_f32 v87, v94, v95
	v_add_f32_e32 v157, v157, v182
	v_add_f32_e32 v156, v156, v162
	s_setprio 1
	s_waitcnt lgkmcnt(6)
	v_mfma_f32_32x32x16_bf16 v[64:79], v[248:251], v[96:99], v[64:79]
	v_mfma_f32_32x32x16_bf16 v[32:47], v[248:251], v[80:83], v[32:47]
	s_waitcnt lgkmcnt(4)
	v_mfma_f32_32x32x16_bf16 v[48:63], v[158:161], v[96:99], v[48:63]
	v_mfma_f32_32x32x16_bf16 v[16:31], v[158:161], v[80:83], v[16:31]
	ds_read_b128 v[248:251], v180 offset:6656
	ds_read_b128 v[158:161], v180 offset:6688
	s_waitcnt lgkmcnt(4)
	v_mfma_f32_32x32x16_bf16 v[64:79], v[104:107], v[100:103], v[64:79]
	s_waitcnt lgkmcnt(2)
	v_mfma_f32_32x32x16_bf16 v[48:63], v[108:111], v[100:103], v[48:63]
	v_mfma_f32_32x32x16_bf16 v[32:47], v[104:107], v[84:87], v[32:47]
	v_mfma_f32_32x32x16_bf16 v[16:31], v[108:111], v[84:87], v[16:31]
	s_setprio 1
	s_waitcnt lgkmcnt(1)
	v_mfma_f32_32x32x16_bf16 v[96:111], v[248:251], v[132:135], v[0:15]
	v_mfma_f32_32x32x16_bf16 v[80:95], v[248:251], v[214:217], v[0:15]
	ds_read_b128 v[248:251], v180 offset:6720
	s_waitcnt lgkmcnt(1)
; #define LAS __attribute__((address_space(3)))
; __device__ __forceinline__ unsigned pk2(float lo, float hi) { f32x2_t v = {lo, hi}; bf16x2_t b = __builtin_convertvector(v, bf16x2_t); return __builtin_bit_cast(unsigned, b); }
; #define MFMA32(a, b, c) __builtin_amdgcn_mfma_f32_32x32x16_bf16((a), (b), (c), 0, 0, 0)
; __device__ __forceinline__ void attn_unit64(const bf16_t* Q, const bf16_t* K, const bf16_t* Vt, bf16_t* O, int bh, int qb8, float mfix, LAS unsigned char* lds) {
;     ...
;                 for (int d0 = 0; d0 < 6; ++d0) { const bf16x8 a = *(const LAS bf16x8*)(kp + half * 32 * 104 + 16 * d0); const bf16x8 qa_ = Qs[512 * d0], qb_ = Qs[512 * (6 + d0)]; sA = MFMA32(a, qa_, sA); sB = MFMA32(a, qb_, sB); }
;                 if (t == tmaxw) {
;                     const int rowA = qw + r, rowB = qw + 32 + r;
; #pragma unroll
;                     for (int i = 0; i < 16; ++i) { const int kv = 64 * t + 32 * half + crow(i, hh); if (kv > rowA) sA[i] = -1e30f; if (kv > rowB) sB[i] = -1e30f; }
;                 }
;                 float la = 0.f, lb_ = 0.f;
; #pragma unroll
;                 for (int i = 0; i < 16; ++i) { sA[i] = __builtin_amdgcn_exp2f(sA[i]); sB[i] = __builtin_amdgcn_exp2f(sB[i]); la += sA[i]; lb_ += sB[i]; }
;                 lA += la; lB += lb_;
;                 u32x4 pwA[2], pwB[2];
; #pragma unroll
;                 for (int e = 0; e < 4; ++e) { pwA[0][e] = pk2(sA[2 * e], sA[2 * e + 1]); pwA[1][e] = pk2(sA[8 + 2 * e], sA[8 + 2 * e + 1]); pwB[0][e] = pk2(sB[2 * e], sB[2 * e + 1]); pwB[1][e] = pk2(sB[8 + 2 * e], sB[8 + 2 * e + 1]); }
; #pragma unroll
;                 for (int k2 = 0; k2 < 2; ++k2) { const int ks = 2 * half + k2;
;                     const u32x2 va0 = *(const LAS u32x2*)(vp + 16 * ks), va1 = *(const LAS u32x2*)(vp + 16 * ks + 8), vb0 = *(const LAS u32x2*)(vp + 32 * 68 + 16 * ks), vb1 = *(const LAS u32x2*)(vp + 32 * 68 + 16 * ks + 8);
;                     const bf16x8 v0 = __builtin_bit_cast(bf16x8, (u32x4){va0[0], va0[1], va1[0], va1[1]}), v1 = __builtin_bit_cast(bf16x8, (u32x4){vb0[0], vb0[1], vb1[0], vb1[1]});
;                     const bf16x8 pfA = __builtin_bit_cast(bf16x8, pwA[k2]), pfB = __builtin_bit_cast(bf16x8, pwB[k2]);
;                     oA0 = MFMA32(v0, pfA, oA0); oA1 = MFMA32(v1, pfA, oA1); oB0 = MFMA32(v0, pfB, oB0); oB1 = MFMA32(v1, pfB, oB1); }
	v_mfma_f32_32x32x16_bf16 v[96:111], v[158:161], v[136:139], v[96:111]
	v_mfma_f32_32x32x16_bf16 v[80:95], v[158:161], v[218:221], v[80:95]
	ds_read_b128 v[158:161], v180 offset:6752
	s_waitcnt lgkmcnt(1)
	v_mfma_f32_32x32x16_bf16 v[96:111], v[248:251], v[140:143], v[96:111]
	v_mfma_f32_32x32x16_bf16 v[80:95], v[248:251], v[232:235], v[80:95]
	ds_read_b128 v[248:251], v180 offset:6784
	s_waitcnt lgkmcnt(1)
	v_mfma_f32_32x32x16_bf16 v[96:111], v[158:161], v[144:147], v[96:111]
	v_mfma_f32_32x32x16_bf16 v[80:95], v[158:161], v[236:239], v[80:95]
	ds_read_b128 v[158:161], v180 offset:6816
	s_waitcnt lgkmcnt(1)
	v_mfma_f32_32x32x16_bf16 v[96:111], v[248:251], v[206:209], v[96:111]
	v_mfma_f32_32x32x16_bf16 v[80:95], v[248:251], v[240:243], v[80:95]
	s_waitcnt lgkmcnt(0)
	v_mfma_f32_32x32x16_bf16 v[96:111], v[158:161], v[210:213], v[96:111]
	v_mfma_f32_32x32x16_bf16 v[80:95], v[158:161], v[244:247], v[80:95]
	ds_read_b64 v[248:249], v178 offset:64
	ds_read_b64 v[250:251], v178 offset:80
	ds_read_b64 v[158:159], v178 offset:4416
	ds_read_b64 v[160:161], v178 offset:4432
	s_setprio 0
	s_nop 5
	v_exp_f32_e32 v96, v96
	v_exp_f32_e32 v97, v97
	v_exp_f32_e32 v98, v98
	v_exp_f32_e32 v99, v99
	v_add_f32_e32 v182, v96, v97
	v_cvt_pk_bf16_f32 v96, v96, v97
	v_exp_f32_e32 v100, v100
	v_exp_f32_e32 v101, v101
	v_add_f32_e32 v182, v182, v98
	v_add_f32_e32 v182, v182, v99
	v_cvt_pk_bf16_f32 v97, v98, v99
	v_exp_f32_e32 v102, v102
	v_exp_f32_e32 v103, v103
	v_add_f32_e32 v182, v182, v100
	v_add_f32_e32 v182, v182, v101
	v_cvt_pk_bf16_f32 v98, v100, v101
	v_exp_f32_e32 v80, v80
	v_exp_f32_e32 v81, v81
	v_add_f32_e32 v182, v182, v102
	v_add_f32_e32 v182, v182, v103
	v_cvt_pk_bf16_f32 v99, v102, v103
	v_exp_f32_e32 v82, v82
	v_exp_f32_e32 v83, v83
	v_add_f32_e32 v162, v80, v81
	v_cvt_pk_bf16_f32 v80, v80, v81
	v_exp_f32_e32 v84, v84
	v_exp_f32_e32 v85, v85
	v_add_f32_e32 v162, v162, v82
	v_add_f32_e32 v162, v162, v83
	v_cvt_pk_bf16_f32 v81, v82, v83
	v_exp_f32_e32 v86, v86
	v_exp_f32_e32 v87, v87
	v_add_f32_e32 v162, v162, v84
	v_add_f32_e32 v162, v162, v85
	v_cvt_pk_bf16_f32 v82, v84, v85
	v_exp_f32_e32 v104, v104
	v_exp_f32_e32 v105, v105
	v_add_f32_e32 v162, v162, v86
	v_add_f32_e32 v162, v162, v87
	v_cvt_pk_bf16_f32 v83, v86, v87
	v_exp_f32_e32 v106, v106
	v_exp_f32_e32 v107, v107
	v_add_f32_e32 v182, v182, v104
	v_add_f32_e32 v182, v182, v105
	v_cvt_pk_bf16_f32 v100, v104, v105
	v_exp_f32_e32 v108, v108
	v_exp_f32_e32 v109, v109
	v_add_f32_e32 v182, v182, v106
	v_add_f32_e32 v182, v182, v107
	v_cvt_pk_bf16_f32 v101, v106, v107
	v_exp_f32_e32 v110, v110
	v_exp_f32_e32 v111, v111
	v_add_f32_e32 v182, v182, v108
	v_add_f32_e32 v182, v182, v109
	v_cvt_pk_bf16_f32 v102, v108, v109
	v_exp_f32_e32 v88, v88
	v_exp_f32_e32 v89, v89
	v_add_f32_e32 v182, v182, v110
	v_add_f32_e32 v182, v182, v111
	v_cvt_pk_bf16_f32 v103, v110, v111
	ds_read_b64 v[104:105], v178 offset:96
	ds_read_b64 v[106:107], v178 offset:112
	ds_read_b64 v[108:109], v178 offset:4448
	ds_read_b64 v[110:111], v178 offset:4464
	v_exp_f32_e32 v90, v90
	v_exp_f32_e32 v91, v91
	v_add_f32_e32 v162, v162, v88
	v_add_f32_e32 v162, v162, v89
	v_cvt_pk_bf16_f32 v84, v88, v89
	v_exp_f32_e32 v92, v92
	v_exp_f32_e32 v93, v93
	v_add_f32_e32 v162, v162, v90
	v_add_f32_e32 v162, v162, v91
	v_cvt_pk_bf16_f32 v85, v90, v91
	v_exp_f32_e32 v94, v94
	v_exp_f32_e32 v95, v95
	v_add_f32_e32 v162, v162, v92
	v_add_f32_e32 v162, v162, v93
	v_cvt_pk_bf16_f32 v86, v92, v93
	v_add_f32_e32 v162, v162, v94
	v_add_f32_e32 v162, v162, v95
	v_cvt_pk_bf16_f32 v87, v94, v95
	v_add_f32_e32 v157, v157, v182
	v_add_f32_e32 v156, v156, v162
	s_setprio 1
	s_waitcnt lgkmcnt(6)
	v_mfma_f32_32x32x16_bf16 v[64:79], v[248:251], v[96:99], v[64:79]
	v_mfma_f32_32x32x16_bf16 v[32:47], v[248:251], v[80:83], v[32:47]
	s_waitcnt lgkmcnt(4)
	v_mfma_f32_32x32x16_bf16 v[48:63], v[158:161], v[96:99], v[48:63]
	v_mfma_f32_32x32x16_bf16 v[16:31], v[158:161], v[80:83], v[16:31]
	s_waitcnt lgkmcnt(2)
	v_mfma_f32_32x32x16_bf16 v[64:79], v[104:107], v[100:103], v[64:79]
	s_waitcnt lgkmcnt(0)
	v_mfma_f32_32x32x16_bf16 v[48:63], v[108:111], v[100:103], v[48:63]
	v_mfma_f32_32x32x16_bf16 v[32:47], v[104:107], v[84:87], v[32:47]
	v_mfma_f32_32x32x16_bf16 v[16:31], v[108:111], v[84:87], v[16:31]
	s_setprio 0
	s_branch .Lattn_join_1
.Lattn_fastd_1:
	s_mul_i32 s4, s29, 0x3400
	v_add_u32_e32 v180, s4, v188
	s_mul_i32 s4, s29, 0x2200
	v_add_u32_e32 v177, s4, v198
	v_add_u32_e32 v178, 0x6800, v177
	ds_read_b128 v[248:251], v180
	ds_read_b128 v[158:161], v180 offset:32
	s_cmp_lg_u64 s[20:21], 0
	s_cbranch_scc0 .Lattn_nold_1d
	global_load_dwordx4 v[112:115], v[130:131], off
	s_and_saveexec_b64 s[4:5], s[0:1]
	v_add_co_u32_e32 v252, vcc, 0x2000, v130
	s_nop 1
	v_addc_co_u32_e32 v253, vcc, 0, v131, vcc
	global_load_dwordx4 v[116:119], v[252:253], off
	s_or_b64 exec, exec, s[4:5]
	global_load_dwordx4 v[120:123], v[128:129], off
; #define LAS __attribute__((address_space(3)))
; __device__ __forceinline__ unsigned pk2(float lo, float hi) { f32x2_t v = {lo, hi}; bf16x2_t b = __builtin_convertvector(v, bf16x2_t); return __builtin_bit_cast(unsigned, b); }
; #define MFMA32(a, b, c) __builtin_amdgcn_mfma_f32_32x32x16_bf16((a), (b), (c), 0, 0, 0)
; __device__ __forceinline__ int crow(int r, int hi) { return (r & 3) + 8 * (r >> 2) + 4 * hi; }
; __device__ __forceinline__ void attn_unit64(const bf16_t* Q, const bf16_t* K, const bf16_t* Vt, bf16_t* O, int bh, int qb8, float mfix, LAS unsigned char* lds) {
;     ...
;                 for (int d0 = 0; d0 < 6; ++d0) { const bf16x8 a = *(const LAS bf16x8*)(kp + half * 32 * 104 + 16 * d0); const bf16x8 qa_ = Qs[512 * d0], qb_ = Qs[512 * (6 + d0)]; sA = MFMA32(a, qa_, sA); sB = MFMA32(a, qb_, sB); }
;                 if (t == tmaxw) {
;                     const int rowA = qw + r, rowB = qw + 32 + r;
; #pragma unroll
;                     for (int i = 0; i < 16; ++i) { const int kv = 64 * t + 32 * half + crow(i, hh); if (kv > rowA) sA[i] = -1e30f; if (kv > rowB) sB[i] = -1e30f; }
;                 }
;                 float la = 0.f, lb_ = 0.f;
; #pragma unroll
;                 for (int i = 0; i < 16; ++i) { sA[i] = __builtin_amdgcn_exp2f(sA[i]); sB[i] = __builtin_amdgcn_exp2f(sB[i]); la += sA[i]; lb_ += sB[i]; }
;                 lA += la; lB += lb_;
;                 u32x4 pwA[2], pwB[2];
; #pragma unroll
;                 for (int e = 0; e < 4; ++e) { pwA[0][e] = pk2(sA[2 * e], sA[2 * e + 1]); pwA[1][e] = pk2(sA[8 + 2 * e], sA[8 + 2 * e + 1]); pwB[0][e] = pk2(sB[2 * e], sB[2 * e + 1]); pwB[1][e] = pk2(sB[8 + 2 * e], sB[8 + 2 * e + 1]); }
.Lattn_nold_1d:
	s_nop 3
	s_setprio 1
	s_waitcnt lgkmcnt(1)
	v_mfma_f32_32x32x16_bf16 v[96:111], v[248:251], v[132:135], v[0:15]
	v_mfma_f32_32x32x16_bf16 v[80:95], v[248:251], v[214:217], v[0:15]
	ds_read_b128 v[248:251], v180 offset:64
	s_waitcnt lgkmcnt(1)
	v_mfma_f32_32x32x16_bf16 v[96:111], v[158:161], v[136:139], v[96:111]
	v_mfma_f32_32x32x16_bf16 v[80:95], v[158:161], v[218:221], v[80:95]
	ds_read_b128 v[158:161], v180 offset:96
	s_waitcnt lgkmcnt(1)
	v_mfma_f32_32x32x16_bf16 v[96:111], v[248:251], v[140:143], v[96:111]
	v_mfma_f32_32x32x16_bf16 v[80:95], v[248:251], v[232:235], v[80:95]
	ds_read_b128 v[248:251], v180 offset:128
	s_waitcnt lgkmcnt(1)
	v_mfma_f32_32x32x16_bf16 v[96:111], v[158:161], v[144:147], v[96:111]
	v_mfma_f32_32x32x16_bf16 v[80:95], v[158:161], v[236:239], v[80:95]
	ds_read_b128 v[158:161], v180 offset:160
	s_waitcnt lgkmcnt(1)
	v_mfma_f32_32x32x16_bf16 v[96:111], v[248:251], v[206:209], v[96:111]
	v_mfma_f32_32x32x16_bf16 v[80:95], v[248:251], v[240:243], v[80:95]
	s_waitcnt lgkmcnt(0)
	v_mfma_f32_32x32x16_bf16 v[96:111], v[158:161], v[210:213], v[96:111]
	v_mfma_f32_32x32x16_bf16 v[80:95], v[158:161], v[244:247], v[80:95]
	v_add_u32_e32 v167, s27, v194
	v_sub_u32_e32 v172, v174, v167
	v_sub_u32_e32 v173, v175, v167
	v_cmp_gt_i32_e32 vcc, 0, v172
	v_cmp_gt_i32_e64 s[4:5], 1, v172
	v_cmp_gt_i32_e64 s[100:101], 2, v172
	s_nop 4
	v_cndmask_b32_e64 v96, v96, v176, vcc
	v_cmp_gt_i32_e32 vcc, 3, v172
	v_cndmask_b32_e64 v97, v97, v176, s[4:5]
	v_cmp_gt_i32_e64 s[4:5], 8, v172
	v_cndmask_b32_e64 v98, v98, v176, s[100:101]
	v_cmp_gt_i32_e64 s[100:101], 9, v172
	v_cndmask_b32_e64 v99, v99, v176, vcc
	v_cmp_gt_i32_e32 vcc, 10, v172
	v_cndmask_b32_e64 v100, v100, v176, s[4:5]
	v_cmp_gt_i32_e64 s[4:5], 11, v172
	v_cndmask_b32_e64 v101, v101, v176, s[100:101]
	v_cmp_gt_i32_e64 s[100:101], 16, v172
	v_cndmask_b32_e64 v102, v102, v176, vcc
	v_cmp_gt_i32_e32 vcc, 17, v172
	v_cndmask_b32_e64 v103, v103, v176, s[4:5]
	v_cmp_gt_i32_e64 s[4:5], 18, v172
	v_cndmask_b32_e64 v104, v104, v176, s[100:101]
	v_cmp_gt_i32_e64 s[100:101], 19, v172
	v_cndmask_b32_e64 v105, v105, v176, vcc
	v_cmp_gt_i32_e32 vcc, 24, v172
	v_cndmask_b32_e64 v106, v106, v176, s[4:5]
	v_cmp_gt_i32_e64 s[4:5], 25, v172
	v_cndmask_b32_e64 v107, v107, v176, s[100:101]
	v_cmp_gt_i32_e64 s[100:101], 26, v172
	v_cndmask_b32_e64 v108, v108, v176, vcc
	v_cmp_gt_i32_e32 vcc, 27, v172
	v_cndmask_b32_e64 v109, v109, v176, s[4:5]
	v_cmp_gt_i32_e64 s[4:5], 0, v173
	v_cndmask_b32_e64 v110, v110, v176, s[100:101]
	v_cmp_gt_i32_e64 s[100:101], 1, v173
	v_cndmask_b32_e64 v111, v111, v176, vcc
	v_cmp_gt_i32_e32 vcc, 2, v173
	v_cndmask_b32_e64 v80, v80, v176, s[4:5]
	v_cmp_gt_i32_e64 s[4:5], 3, v173
	v_cndmask_b32_e64 v81, v81, v176, s[100:101]
	v_cmp_gt_i32_e64 s[100:101], 8, v173
	v_cndmask_b32_e64 v82, v82, v176, vcc
	v_cmp_gt_i32_e32 vcc, 9, v173
	v_cndmask_b32_e64 v83, v83, v176, s[4:5]
	v_cmp_gt_i32_e64 s[4:5], 10, v173
	v_cndmask_b32_e64 v84, v84, v176, s[100:101]
	v_cmp_gt_i32_e64 s[100:101], 11, v173
	v_cndmask_b32_e64 v85, v85, v176, vcc
	v_cmp_gt_i32_e32 vcc, 16, v173
	v_cndmask_b32_e64 v86, v86, v176, s[4:5]
	v_cmp_gt_i32_e64 s[4:5], 17, v173
	v_cndmask_b32_e64 v87, v87, v176, s[100:101]
	v_cmp_gt_i32_e64 s[100:101], 18, v173
	v_cndmask_b32_e64 v88, v88, v176, vcc
	v_cmp_gt_i32_e32 vcc, 19, v173
	v_cndmask_b32_e64 v89, v89, v176, s[4:5]
	v_cmp_gt_i32_e64 s[4:5], 24, v173
	v_cndmask_b32_e64 v90, v90, v176, s[100:101]
	v_cmp_gt_i32_e64 s[100:101], 25, v173
	v_cndmask_b32_e64 v91, v91, v176, vcc
	v_cmp_gt_i32_e32 vcc, 26, v173
	v_cndmask_b32_e64 v92, v92, v176, s[4:5]
	v_cmp_gt_i32_e64 s[4:5], 27, v173
	v_cndmask_b32_e64 v93, v93, v176, s[100:101]
	v_cndmask_b32_e64 v94, v94, v176, vcc
	v_cndmask_b32_e64 v95, v95, v176, s[4:5]
	ds_read_b64 v[248:249], v178 offset:0
	ds_read_b64 v[250:251], v178 offset:16
	ds_read_b64 v[158:159], v178 offset:4352
	ds_read_b64 v[160:161], v178 offset:4368
	s_setprio 0
	v_exp_f32_e32 v96, v96
	v_exp_f32_e32 v97, v97
	v_exp_f32_e32 v98, v98
	v_exp_f32_e32 v99, v99
	v_add_f32_e32 v182, v96, v97
	v_cvt_pk_bf16_f32 v96, v96, v97
	v_exp_f32_e32 v100, v100
	v_exp_f32_e32 v101, v101
	v_add_f32_e32 v182, v182, v98
	v_add_f32_e32 v182, v182, v99
	v_cvt_pk_bf16_f32 v97, v98, v99
	v_exp_f32_e32 v102, v102
	v_exp_f32_e32 v103, v103
	v_add_f32_e32 v182, v182, v100
	v_add_f32_e32 v182, v182, v101
	v_cvt_pk_bf16_f32 v98, v100, v101
	v_exp_f32_e32 v80, v80
	v_exp_f32_e32 v81, v81
	v_add_f32_e32 v182, v182, v102
	v_add_f32_e32 v182, v182, v103
	v_cvt_pk_bf16_f32 v99, v102, v103
	v_exp_f32_e32 v82, v82
	v_exp_f32_e32 v83, v83
	v_add_f32_e32 v162, v80, v81
	v_cvt_pk_bf16_f32 v80, v80, v81
	v_exp_f32_e32 v84, v84
	v_exp_f32_e32 v85, v85
	v_add_f32_e32 v162, v162, v82
	v_add_f32_e32 v162, v162, v83
	v_cvt_pk_bf16_f32 v81, v82, v83
	v_exp_f32_e32 v86, v86
	v_exp_f32_e32 v87, v87
	v_add_f32_e32 v162, v162, v84
	v_add_f32_e32 v162, v162, v85
	v_cvt_pk_bf16_f32 v82, v84, v85
	v_exp_f32_e32 v104, v104
	v_exp_f32_e32 v105, v105
	v_add_f32_e32 v162, v162, v86
	v_add_f32_e32 v162, v162, v87
	v_cvt_pk_bf16_f32 v83, v86, v87
	v_exp_f32_e32 v106, v106
	v_exp_f32_e32 v107, v107
	v_add_f32_e32 v182, v182, v104
	v_add_f32_e32 v182, v182, v105
	v_cvt_pk_bf16_f32 v100, v104, v105
	v_exp_f32_e32 v108, v108
	v_exp_f32_e32 v109, v109
	v_add_f32_e32 v182, v182, v106
	v_add_f32_e32 v182, v182, v107
	v_cvt_pk_bf16_f32 v101, v106, v107
	v_exp_f32_e32 v110, v110
	v_exp_f32_e32 v111, v111
	v_add_f32_e32 v182, v182, v108
	v_add_f32_e32 v182, v182, v109
	v_cvt_pk_bf16_f32 v102, v108, v109
	v_exp_f32_e32 v88, v88
	v_exp_f32_e32 v89, v89
	v_add_f32_e32 v182, v182, v110
	v_add_f32_e32 v182, v182, v111
	v_cvt_pk_bf16_f32 v103, v110, v111
	ds_read_b64 v[104:105], v178 offset:32
	ds_read_b64 v[106:107], v178 offset:48
	ds_read_b64 v[108:109], v178 offset:4384
	ds_read_b64 v[110:111], v178 offset:4400
	v_exp_f32_e32 v90, v90
	v_exp_f32_e32 v91, v91
	v_add_f32_e32 v162, v162, v88
	v_add_f32_e32 v162, v162, v89
	v_cvt_pk_bf16_f32 v84, v88, v89
	v_exp_f32_e32 v92, v92
	v_exp_f32_e32 v93, v93
	v_add_f32_e32 v162, v162, v90
	v_add_f32_e32 v162, v162, v91
	v_cvt_pk_bf16_f32 v85, v90, v91
	v_exp_f32_e32 v94, v94
	v_exp_f32_e32 v95, v95
	v_add_f32_e32 v162, v162, v92
	v_add_f32_e32 v162, v162, v93
	v_cvt_pk_bf16_f32 v86, v92, v93
	v_add_f32_e32 v162, v162, v94
	v_add_f32_e32 v162, v162, v95
	v_cvt_pk_bf16_f32 v87, v94, v95
	v_add_f32_e32 v157, v157, v182
	v_add_f32_e32 v156, v156, v162
	s_setprio 1
	s_waitcnt lgkmcnt(6)
; #define LAS __attribute__((address_space(3)))
; __device__ __forceinline__ unsigned pk2(float lo, float hi) { f32x2_t v = {lo, hi}; bf16x2_t b = __builtin_convertvector(v, bf16x2_t); return __builtin_bit_cast(unsigned, b); }
; #define MFMA32(a, b, c) __builtin_amdgcn_mfma_f32_32x32x16_bf16((a), (b), (c), 0, 0, 0)
; __device__ __forceinline__ void attn_unit64(const bf16_t* Q, const bf16_t* K, const bf16_t* Vt, bf16_t* O, int bh, int qb8, float mfix, LAS unsigned char* lds) {
;     ...
;                 for (int d0 = 0; d0 < 6; ++d0) { const bf16x8 a = *(const LAS bf16x8*)(kp + half * 32 * 104 + 16 * d0); const bf16x8 qa_ = Qs[512 * d0], qb_ = Qs[512 * (6 + d0)]; sA = MFMA32(a, qa_, sA); sB = MFMA32(a, qb_, sB); }
;     ...
;                 for (int e = 0; e < 4; ++e) { pwA[0][e] = pk2(sA[2 * e], sA[2 * e + 1]); pwA[1][e] = pk2(sA[8 + 2 * e], sA[8 + 2 * e + 1]); pwB[0][e] = pk2(sB[2 * e], sB[2 * e + 1]); pwB[1][e] = pk2(sB[8 + 2 * e], sB[8 + 2 * e + 1]); }
; #pragma unroll
;                 for (int k2 = 0; k2 < 2; ++k2) { const int ks = 2 * half + k2;
;                     const u32x2 va0 = *(const LAS u32x2*)(vp + 16 * ks), va1 = *(const LAS u32x2*)(vp + 16 * ks + 8), vb0 = *(const LAS u32x2*)(vp + 32 * 68 + 16 * ks), vb1 = *(const LAS u32x2*)(vp + 32 * 68 + 16 * ks + 8);
;                     const bf16x8 v0 = __builtin_bit_cast(bf16x8, (u32x4){va0[0], va0[1], va1[0], va1[1]}), v1 = __builtin_bit_cast(bf16x8, (u32x4){vb0[0], vb0[1], vb1[0], vb1[1]});
;                     const bf16x8 pfA = __builtin_bit_cast(bf16x8, pwA[k2]), pfB = __builtin_bit_cast(bf16x8, pwB[k2]);
;                     oA0 = MFMA32(v0, pfA, oA0); oA1 = MFMA32(v1, pfA, oA1); oB0 = MFMA32(v0, pfB, oB0); oB1 = MFMA32(v1, pfB, oB1); }
	v_mfma_f32_32x32x16_bf16 v[64:79], v[248:251], v[96:99], v[64:79]
	v_mfma_f32_32x32x16_bf16 v[32:47], v[248:251], v[80:83], v[32:47]
	s_waitcnt lgkmcnt(4)
	v_mfma_f32_32x32x16_bf16 v[48:63], v[158:161], v[96:99], v[48:63]
	v_mfma_f32_32x32x16_bf16 v[16:31], v[158:161], v[80:83], v[16:31]
	ds_read_b128 v[248:251], v180 offset:6656
	ds_read_b128 v[158:161], v180 offset:6688
	s_waitcnt lgkmcnt(4)
	v_mfma_f32_32x32x16_bf16 v[64:79], v[104:107], v[100:103], v[64:79]
	s_waitcnt lgkmcnt(2)
	v_mfma_f32_32x32x16_bf16 v[48:63], v[108:111], v[100:103], v[48:63]
	v_mfma_f32_32x32x16_bf16 v[32:47], v[104:107], v[84:87], v[32:47]
	v_mfma_f32_32x32x16_bf16 v[16:31], v[108:111], v[84:87], v[16:31]
	s_setprio 1
	s_waitcnt lgkmcnt(1)
	v_mfma_f32_32x32x16_bf16 v[96:111], v[248:251], v[132:135], v[0:15]
	v_mfma_f32_32x32x16_bf16 v[80:95], v[248:251], v[214:217], v[0:15]
	ds_read_b128 v[248:251], v180 offset:6720
	s_waitcnt lgkmcnt(1)
	v_mfma_f32_32x32x16_bf16 v[96:111], v[158:161], v[136:139], v[96:111]
	v_mfma_f32_32x32x16_bf16 v[80:95], v[158:161], v[218:221], v[80:95]
	ds_read_b128 v[158:161], v180 offset:6752
	s_waitcnt lgkmcnt(1)
	v_mfma_f32_32x32x16_bf16 v[96:111], v[248:251], v[140:143], v[96:111]
	v_mfma_f32_32x32x16_bf16 v[80:95], v[248:251], v[232:235], v[80:95]
	ds_read_b128 v[248:251], v180 offset:6784
	s_waitcnt lgkmcnt(1)
	v_mfma_f32_32x32x16_bf16 v[96:111], v[158:161], v[144:147], v[96:111]
	v_mfma_f32_32x32x16_bf16 v[80:95], v[158:161], v[236:239], v[80:95]
	ds_read_b128 v[158:161], v180 offset:6816
	s_waitcnt lgkmcnt(1)
	v_mfma_f32_32x32x16_bf16 v[96:111], v[248:251], v[206:209], v[96:111]
	v_mfma_f32_32x32x16_bf16 v[80:95], v[248:251], v[240:243], v[80:95]
	s_waitcnt lgkmcnt(0)
; #define LAS __attribute__((address_space(3)))
; __device__ __forceinline__ unsigned pk2(float lo, float hi) { f32x2_t v = {lo, hi}; bf16x2_t b = __builtin_convertvector(v, bf16x2_t); return __builtin_bit_cast(unsigned, b); }
; #define MFMA32(a, b, c) __builtin_amdgcn_mfma_f32_32x32x16_bf16((a), (b), (c), 0, 0, 0)
; __device__ __forceinline__ int crow(int r, int hi) { return (r & 3) + 8 * (r >> 2) + 4 * hi; }
; __device__ __forceinline__ void attn_unit64(const bf16_t* Q, const bf16_t* K, const bf16_t* Vt, bf16_t* O, int bh, int qb8, float mfix, LAS unsigned char* lds) {
;     ...
;                 if (t == tmaxw) {
;                     const int rowA = qw + r, rowB = qw + 32 + r;
; #pragma unroll
;                     for (int i = 0; i < 16; ++i) { const int kv = 64 * t + 32 * half + crow(i, hh); if (kv > rowA) sA[i] = -1e30f; if (kv > rowB) sB[i] = -1e30f; }
;                 }
;                 float la = 0.f, lb_ = 0.f;
; #pragma unroll
;                 for (int i = 0; i < 16; ++i) { sA[i] = __builtin_amdgcn_exp2f(sA[i]); sB[i] = __builtin_amdgcn_exp2f(sB[i]); la += sA[i]; lb_ += sB[i]; }
;                 lA += la; lB += lb_;
;                 u32x4 pwA[2], pwB[2];
; #pragma unroll
;                 for (int e = 0; e < 4; ++e) { pwA[0][e] = pk2(sA[2 * e], sA[2 * e + 1]); pwA[1][e] = pk2(sA[8 + 2 * e], sA[8 + 2 * e + 1]); pwB[0][e] = pk2(sB[2 * e], sB[2 * e + 1]); pwB[1][e] = pk2(sB[8 + 2 * e], sB[8 + 2 * e + 1]); }
; #pragma unroll
;                 for (int k2 = 0; k2 < 2; ++k2) { const int ks = 2 * half + k2;
;                     const u32x2 va0 = *(const LAS u32x2*)(vp + 16 * ks), va1 = *(const LAS u32x2*)(vp + 16 * ks + 8), vb0 = *(const LAS u32x2*)(vp + 32 * 68 + 16 * ks), vb1 = *(const LAS u32x2*)(vp + 32 * 68 + 16 * ks + 8);
;                     const bf16x8 v0 = __builtin_bit_cast(bf16x8, (u32x4){va0[0], va0[1], va1[0], va1[1]}), v1 = __builtin_bit_cast(bf16x8, (u32x4){vb0[0], vb0[1], vb1[0], vb1[1]});
;                     const bf16x8 pfA = __builtin_bit_cast(bf16x8, pwA[k2]), pfB = __builtin_bit_cast(bf16x8, pwB[k2]);
;                     oA0 = MFMA32(v0, pfA, oA0); oA1 = MFMA32(v1, pfA, oA1); oB0 = MFMA32(v0, pfB, oB0); oB1 = MFMA32(v1, pfB, oB1); }
;                 __builtin_amdgcn_sched_barrier(0);
	v_mfma_f32_32x32x16_bf16 v[96:111], v[158:161], v[210:213], v[96:111]
	v_mfma_f32_32x32x16_bf16 v[80:95], v[158:161], v[244:247], v[80:95]
	v_cmp_gt_i32_e32 vcc, 32, v172
	v_cmp_gt_i32_e64 s[4:5], 33, v172
	v_cmp_gt_i32_e64 s[100:101], 34, v172
	s_nop 7
	v_cndmask_b32_e64 v96, v96, v176, vcc
	v_cmp_gt_i32_e32 vcc, 35, v172
	v_cndmask_b32_e64 v97, v97, v176, s[4:5]
	v_cmp_gt_i32_e64 s[4:5], 40, v172
	v_cndmask_b32_e64 v98, v98, v176, s[100:101]
	v_cmp_gt_i32_e64 s[100:101], 41, v172
	v_cndmask_b32_e64 v99, v99, v176, vcc
	v_cmp_gt_i32_e32 vcc, 42, v172
	v_cndmask_b32_e64 v100, v100, v176, s[4:5]
	v_cmp_gt_i32_e64 s[4:5], 43, v172
	v_cndmask_b32_e64 v101, v101, v176, s[100:101]
	v_cmp_gt_i32_e64 s[100:101], 48, v172
	v_cndmask_b32_e64 v102, v102, v176, vcc
	v_cmp_gt_i32_e32 vcc, 49, v172
	v_cndmask_b32_e64 v103, v103, v176, s[4:5]
	v_cmp_gt_i32_e64 s[4:5], 50, v172
	v_cndmask_b32_e64 v104, v104, v176, s[100:101]
	v_cmp_gt_i32_e64 s[100:101], 51, v172
	v_cndmask_b32_e64 v105, v105, v176, vcc
	v_cmp_gt_i32_e32 vcc, 56, v172
	v_cndmask_b32_e64 v106, v106, v176, s[4:5]
	v_cmp_gt_i32_e64 s[4:5], 57, v172
	v_cndmask_b32_e64 v107, v107, v176, s[100:101]
	v_cmp_gt_i32_e64 s[100:101], 58, v172
	v_cndmask_b32_e64 v108, v108, v176, vcc
	v_cmp_gt_i32_e32 vcc, 59, v172
	v_cndmask_b32_e64 v109, v109, v176, s[4:5]
	v_cmp_gt_i32_e64 s[4:5], 32, v173
	v_cndmask_b32_e64 v110, v110, v176, s[100:101]
	v_cmp_gt_i32_e64 s[100:101], 33, v173
	v_cndmask_b32_e64 v111, v111, v176, vcc
	v_cmp_gt_i32_e32 vcc, 34, v173
	v_cndmask_b32_e64 v80, v80, v176, s[4:5]
	v_cmp_gt_i32_e64 s[4:5], 35, v173
	v_cndmask_b32_e64 v81, v81, v176, s[100:101]
	v_cmp_gt_i32_e64 s[100:101], 40, v173
	v_cndmask_b32_e64 v82, v82, v176, vcc
	v_cmp_gt_i32_e32 vcc, 41, v173
	v_cndmask_b32_e64 v83, v83, v176, s[4:5]
	v_cmp_gt_i32_e64 s[4:5], 42, v173
	v_cndmask_b32_e64 v84, v84, v176, s[100:101]
	v_cmp_gt_i32_e64 s[100:101], 43, v173
	v_cndmask_b32_e64 v85, v85, v176, vcc
	v_cmp_gt_i32_e32 vcc, 48, v173
	v_cndmask_b32_e64 v86, v86, v176, s[4:5]
	v_cmp_gt_i32_e64 s[4:5], 49, v173
	v_cndmask_b32_e64 v87, v87, v176, s[100:101]
	v_cmp_gt_i32_e64 s[100:101], 50, v173
	v_cndmask_b32_e64 v88, v88, v176, vcc
	v_cmp_gt_i32_e32 vcc, 51, v173
	v_cndmask_b32_e64 v89, v89, v176, s[4:5]
	v_cmp_gt_i32_e64 s[4:5], 56, v173
	v_cndmask_b32_e64 v90, v90, v176, s[100:101]
	v_cmp_gt_i32_e64 s[100:101], 57, v173
	v_cndmask_b32_e64 v91, v91, v176, vcc
	v_cmp_gt_i32_e32 vcc, 58, v173
	v_cndmask_b32_e64 v92, v92, v176, s[4:5]
	v_cmp_gt_i32_e64 s[4:5], 59, v173
	v_cndmask_b32_e64 v93, v93, v176, s[100:101]
	v_cndmask_b32_e64 v94, v94, v176, vcc
	v_cndmask_b32_e64 v95, v95, v176, s[4:5]
	ds_read_b64 v[248:249], v178 offset:64
	ds_read_b64 v[250:251], v178 offset:80
	ds_read_b64 v[158:159], v178 offset:4416
	ds_read_b64 v[160:161], v178 offset:4432
	s_setprio 0
	v_exp_f32_e32 v96, v96
	v_exp_f32_e32 v97, v97
	v_exp_f32_e32 v98, v98
	v_exp_f32_e32 v99, v99
	v_add_f32_e32 v182, v96, v97
	v_cvt_pk_bf16_f32 v96, v96, v97
	v_exp_f32_e32 v100, v100
	v_exp_f32_e32 v101, v101
	v_add_f32_e32 v182, v182, v98
	v_add_f32_e32 v182, v182, v99
	v_cvt_pk_bf16_f32 v97, v98, v99
	v_exp_f32_e32 v102, v102
	v_exp_f32_e32 v103, v103
	v_add_f32_e32 v182, v182, v100
	v_add_f32_e32 v182, v182, v101
	v_cvt_pk_bf16_f32 v98, v100, v101
	v_exp_f32_e32 v80, v80
	v_exp_f32_e32 v81, v81
	v_add_f32_e32 v182, v182, v102
	v_add_f32_e32 v182, v182, v103
	v_cvt_pk_bf16_f32 v99, v102, v103
	v_exp_f32_e32 v82, v82
	v_exp_f32_e32 v83, v83
	v_add_f32_e32 v162, v80, v81
	v_cvt_pk_bf16_f32 v80, v80, v81
	v_exp_f32_e32 v84, v84
	v_exp_f32_e32 v85, v85
	v_add_f32_e32 v162, v162, v82
	v_add_f32_e32 v162, v162, v83
	v_cvt_pk_bf16_f32 v81, v82, v83
	v_exp_f32_e32 v86, v86
	v_exp_f32_e32 v87, v87
	v_add_f32_e32 v162, v162, v84
	v_add_f32_e32 v162, v162, v85
	v_cvt_pk_bf16_f32 v82, v84, v85
	v_exp_f32_e32 v104, v104
	v_exp_f32_e32 v105, v105
	v_add_f32_e32 v162, v162, v86
	v_add_f32_e32 v162, v162, v87
	v_cvt_pk_bf16_f32 v83, v86, v87
	v_exp_f32_e32 v106, v106
	v_exp_f32_e32 v107, v107
	v_add_f32_e32 v182, v182, v104
	v_add_f32_e32 v182, v182, v105
	v_cvt_pk_bf16_f32 v100, v104, v105
	v_exp_f32_e32 v108, v108
	v_exp_f32_e32 v109, v109
	v_add_f32_e32 v182, v182, v106
	v_add_f32_e32 v182, v182, v107
	v_cvt_pk_bf16_f32 v101, v106, v107
	v_exp_f32_e32 v110, v110
	v_exp_f32_e32 v111, v111
	v_add_f32_e32 v182, v182, v108
	v_add_f32_e32 v182, v182, v109
	v_cvt_pk_bf16_f32 v102, v108, v109
	v_exp_f32_e32 v88, v88
	v_exp_f32_e32 v89, v89
	v_add_f32_e32 v182, v182, v110
	v_add_f32_e32 v182, v182, v111
	v_cvt_pk_bf16_f32 v103, v110, v111
	ds_read_b64 v[104:105], v178 offset:96
	ds_read_b64 v[106:107], v178 offset:112
	ds_read_b64 v[108:109], v178 offset:4448
	ds_read_b64 v[110:111], v178 offset:4464
	v_exp_f32_e32 v90, v90
	v_exp_f32_e32 v91, v91
	v_add_f32_e32 v162, v162, v88
	v_add_f32_e32 v162, v162, v89
	v_cvt_pk_bf16_f32 v84, v88, v89
	v_exp_f32_e32 v92, v92
	v_exp_f32_e32 v93, v93
	v_add_f32_e32 v162, v162, v90
	v_add_f32_e32 v162, v162, v91
	v_cvt_pk_bf16_f32 v85, v90, v91
	v_exp_f32_e32 v94, v94
	v_exp_f32_e32 v95, v95
	v_add_f32_e32 v162, v162, v92
	v_add_f32_e32 v162, v162, v93
	v_cvt_pk_bf16_f32 v86, v92, v93
	v_add_f32_e32 v162, v162, v94
	v_add_f32_e32 v162, v162, v95
	v_cvt_pk_bf16_f32 v87, v94, v95
	v_add_f32_e32 v157, v157, v182
	v_add_f32_e32 v156, v156, v162
	s_setprio 1
	s_waitcnt lgkmcnt(6)
	v_mfma_f32_32x32x16_bf16 v[64:79], v[248:251], v[96:99], v[64:79]
	v_mfma_f32_32x32x16_bf16 v[32:47], v[248:251], v[80:83], v[32:47]
	s_waitcnt lgkmcnt(4)
	v_mfma_f32_32x32x16_bf16 v[48:63], v[158:161], v[96:99], v[48:63]
	v_mfma_f32_32x32x16_bf16 v[16:31], v[158:161], v[80:83], v[16:31]
	s_waitcnt lgkmcnt(2)
	v_mfma_f32_32x32x16_bf16 v[64:79], v[104:107], v[100:103], v[64:79]
	s_waitcnt lgkmcnt(0)
	v_mfma_f32_32x32x16_bf16 v[48:63], v[108:111], v[100:103], v[48:63]
	v_mfma_f32_32x32x16_bf16 v[32:47], v[104:107], v[84:87], v[32:47]
	v_mfma_f32_32x32x16_bf16 v[16:31], v[108:111], v[84:87], v[16:31]
	s_setprio 0
	s_branch .Lattn_join_1

; #define ATT_LOADG(t) do { kA = *(const u32x4*)(Kh + (size_t)(t) * 6144 + tid * 8); if (tid < 256) kB = *(const u32x4*)(Kh + (size_t)(t) * 6144 + c2 * 8); \
;         vA = *(const u32x4*)(Vh + (size_t)vr * T + 64 * (t) + vc * 8); } while (0)
; #define ATT_LOADG(t) do { kA = *(const u32x4*)(Kh + (size_t)(t) * 6144 + tid * 8); if (tid < 256) kB = *(const u32x4*)(Kh + (size_t)(t) * 6144 + c2 * 8); \
;         vA = *(const u32x4*)(Vh + (size_t)vr * T + 64 * (t) + vc * 8); } while (0)
; __device__ __forceinline__ void attn_unit64(const bf16_t* Q, const bf16_t* K, const bf16_t* Vt, bf16_t* O, int bh, int qb8, float mfix, LAS unsigned char* lds) {
;     ...
;     for (int t = 0; t < NTL; ++t) {
;         const int buf = t & 1;
;         if (t + 1 < NTL) ATT_LOADG(t + 1);
;         if (t <= tmaxw) {
.LBB0_814:
	s_cmp_le_u32 s33, s24
	s_cbranch_scc1 .Lattn_fast_2
	s_add_i32 s28, s33, 1
	s_cmp_lt_u32 s28, s25
	s_cselect_b64 s[20:21], -1, 0
	s_cmp_ge_u32 s28, s25
	s_cbranch_scc1 .LBB0_819
	global_load_dwordx4 v[112:115], v[124:125], off
	s_and_saveexec_b64 s[4:5], s[0:1]
	s_cbranch_execz .LBB0_817
	v_add_co_u32_e32 v80, vcc, 0x2000, v124
	s_nop 1
	v_addc_co_u32_e32 v81, vcc, 0, v125, vcc
	global_load_dwordx4 v[116:119], v[80:81], off

; #define LAS __attribute__((address_space(3)))
; #define MFMA32(a, b, c) __builtin_amdgcn_mfma_f32_32x32x16_bf16((a), (b), (c), 0, 0, 0)
; #define ATT_LOADG(t) do { kA = *(const u32x4*)(Kh + (size_t)(t) * 6144 + tid * 8); if (tid < 256) kB = *(const u32x4*)(Kh + (size_t)(t) * 6144 + c2 * 8); \
;         vA = *(const u32x4*)(Vh + (size_t)vr * T + 64 * (t) + vc * 8); } while (0)
; #define ATT_LOADG(t) do { kA = *(const u32x4*)(Kh + (size_t)(t) * 6144 + tid * 8); if (tid < 256) kB = *(const u32x4*)(Kh + (size_t)(t) * 6144 + c2 * 8); \
;         vA = *(const u32x4*)(Vh + (size_t)vr * T + 64 * (t) + vc * 8); } while (0)
; __device__ __forceinline__ void attn_unit64(const bf16_t* Q, const bf16_t* K, const bf16_t* Vt, bf16_t* O, int bh, int qb8, float mfix, LAS unsigned char* lds) {
;     ...
;         const int buf = t & 1;
;         if (t + 1 < NTL) ATT_LOADG(t + 1);
;         if (t <= tmaxw) {
;             const LAS bf16_t* kp = Kb + buf * 6656 + r * 104 + 8 * hh;
;             const LAS bf16_t* vp = Vb + buf * 4352 + r * 68 + 4 * hh;
; #pragma unroll
;             for (int half = 0; half < 2; ++half) {
;                 f32x16 sA, sB;
; #pragma unroll
;                 for (int i = 0; i < 16; ++i) { sA[i] = -mfix; sB[i] = -mfix; }
; #pragma unroll
;                 for (int d0 = 0; d0 < 6; ++d0) { const bf16x8 a = *(const LAS bf16x8*)(kp + half * 32 * 104 + 16 * d0); const bf16x8 qa_ = Qs[512 * d0], qb_ = Qs[512 * (6 + d0)]; sA = MFMA32(a, qa_, sA); sB = MFMA32(a, qb_, sB); }
.Lattn_fast_2:
	s_add_i32 s28, s33, 1
	s_cmp_lt_u32 s28, s25
	s_cselect_b64 s[20:21], -1, 0
	s_and_b32 s29, s33, 1
	s_cmp_eq_u32 s33, s24
	s_cbranch_scc1 .Lattn_fastd_2
	s_mul_i32 s4, s29, 0x3400
	v_add_u32_e32 v180, s4, v188
	s_mul_i32 s4, s29, 0x2200
	v_add_u32_e32 v177, s4, v198
	v_add_u32_e32 v178, 0x6800, v177
	ds_read_b128 v[248:251], v180
	ds_read_b128 v[158:161], v180 offset:32
	s_cmp_lg_u64 s[20:21], 0
	s_cbranch_scc0 .Lattn_nold_2n
	global_load_dwordx4 v[112:115], v[124:125], off
	s_and_saveexec_b64 s[4:5], s[0:1]
	v_add_co_u32_e32 v252, vcc, 0x2000, v124
	s_nop 1
	v_addc_co_u32_e32 v253, vcc, 0, v125, vcc
	global_load_dwordx4 v[116:119], v[252:253], off
	s_or_b64 exec, exec, s[4:5]
	global_load_dwordx4 v[120:123], v[126:127], off
.Lattn_nold_2n:
	s_nop 3
	s_setprio 1
	s_waitcnt lgkmcnt(1)
	v_mfma_f32_32x32x16_bf16 v[96:111], v[248:251], v[132:135], v[0:15]
	v_mfma_f32_32x32x16_bf16 v[80:95], v[248:251], v[214:217], v[0:15]
	ds_read_b128 v[248:251], v180 offset:64
	s_waitcnt lgkmcnt(1)
	v_mfma_f32_32x32x16_bf16 v[96:111], v[158:161], v[136:139], v[96:111]
	v_mfma_f32_32x32x16_bf16 v[80:95], v[158:161], v[218:221], v[80:95]
	ds_read_b128 v[158:161], v180 offset:96
	s_waitcnt lgkmcnt(1)
	v_mfma_f32_32x32x16_bf16 v[96:111], v[248:251], v[140:143], v[96:111]
	v_mfma_f32_32x32x16_bf16 v[80:95], v[248:251], v[232:235], v[80:95]
	ds_read_b128 v[248:251], v180 offset:128
	s_waitcnt lgkmcnt(1)
	v_mfma_f32_32x32x16_bf16 v[96:111], v[158:161], v[144:147], v[96:111]
	v_mfma_f32_32x32x16_bf16 v[80:95], v[158:161], v[236:239], v[80:95]
	ds_read_b128 v[158:161], v180 offset:160
	s_waitcnt lgkmcnt(1)
	v_mfma_f32_32x32x16_bf16 v[96:111], v[248:251], v[206:209], v[96:111]
	v_mfma_f32_32x32x16_bf16 v[80:95], v[248:251], v[240:243], v[80:95]
	s_waitcnt lgkmcnt(0)
	v_mfma_f32_32x32x16_bf16 v[96:111], v[158:161], v[210:213], v[96:111]
	v_mfma_f32_32x32x16_bf16 v[80:95], v[158:161], v[244:247], v[80:95]
	ds_read_b64 v[248:249], v178 offset:0
	ds_read_b64 v[250:251], v178 offset:16
	ds_read_b64 v[158:159], v178 offset:4352
	ds_read_b64 v[160:161], v178 offset:4368
	s_setprio 0
	s_nop 5
	v_exp_f32_e32 v96, v96
	v_exp_f32_e32 v97, v97
	v_exp_f32_e32 v98, v98
	v_exp_f32_e32 v99, v99
	v_add_f32_e32 v182, v96, v97
	v_cvt_pk_bf16_f32 v96, v96, v97
	v_exp_f32_e32 v100, v100
	v_exp_f32_e32 v101, v101
	v_add_f32_e32 v182, v182, v98
	v_add_f32_e32 v182, v182, v99
	v_cvt_pk_bf16_f32 v97, v98, v99
	v_exp_f32_e32 v102, v102
	v_exp_f32_e32 v103, v103
	v_add_f32_e32 v182, v182, v100
	v_add_f32_e32 v182, v182, v101
	v_cvt_pk_bf16_f32 v98, v100, v101
	v_exp_f32_e32 v80, v80
	v_exp_f32_e32 v81, v81
	v_add_f32_e32 v182, v182, v102
	v_add_f32_e32 v182, v182, v103
	v_cvt_pk_bf16_f32 v99, v102, v103
	v_exp_f32_e32 v82, v82
	v_exp_f32_e32 v83, v83
	v_add_f32_e32 v162, v80, v81
	v_cvt_pk_bf16_f32 v80, v80, v81
	v_exp_f32_e32 v84, v84
	v_exp_f32_e32 v85, v85
	v_add_f32_e32 v162, v162, v82
	v_add_f32_e32 v162, v162, v83
	v_cvt_pk_bf16_f32 v81, v82, v83
	v_exp_f32_e32 v86, v86
	v_exp_f32_e32 v87, v87
	v_add_f32_e32 v162, v162, v84
	v_add_f32_e32 v162, v162, v85
	v_cvt_pk_bf16_f32 v82, v84, v85
	v_exp_f32_e32 v104, v104
	v_exp_f32_e32 v105, v105
	v_add_f32_e32 v162, v162, v86
	v_add_f32_e32 v162, v162, v87
	v_cvt_pk_bf16_f32 v83, v86, v87
	v_exp_f32_e32 v106, v106
	v_exp_f32_e32 v107, v107
	v_add_f32_e32 v182, v182, v104
	v_add_f32_e32 v182, v182, v105
	v_cvt_pk_bf16_f32 v100, v104, v105
	v_exp_f32_e32 v108, v108
	v_exp_f32_e32 v109, v109
	v_add_f32_e32 v182, v182, v106
	v_add_f32_e32 v182, v182, v107
	v_cvt_pk_bf16_f32 v101, v106, v107
	v_exp_f32_e32 v110, v110
	v_exp_f32_e32 v111, v111
	v_add_f32_e32 v182, v182, v108
	v_add_f32_e32 v182, v182, v109
	v_cvt_pk_bf16_f32 v102, v108, v109
	v_exp_f32_e32 v88, v88
	v_exp_f32_e32 v89, v89
	v_add_f32_e32 v182, v182, v110
	v_add_f32_e32 v182, v182, v111
	v_cvt_pk_bf16_f32 v103, v110, v111
	ds_read_b64 v[104:105], v178 offset:32
	ds_read_b64 v[106:107], v178 offset:48
	ds_read_b64 v[108:109], v178 offset:4384
	ds_read_b64 v[110:111], v178 offset:4400
	v_exp_f32_e32 v90, v90
	v_exp_f32_e32 v91, v91
	v_add_f32_e32 v162, v162, v88
	v_add_f32_e32 v162, v162, v89
	v_cvt_pk_bf16_f32 v84, v88, v89
	v_exp_f32_e32 v92, v92
	v_exp_f32_e32 v93, v93
	v_add_f32_e32 v162, v162, v90
	v_add_f32_e32 v162, v162, v91
	v_cvt_pk_bf16_f32 v85, v90, v91
	v_exp_f32_e32 v94, v94
	v_exp_f32_e32 v95, v95
	v_add_f32_e32 v162, v162, v92
	v_add_f32_e32 v162, v162, v93
	v_cvt_pk_bf16_f32 v86, v92, v93
	v_add_f32_e32 v162, v162, v94
	v_add_f32_e32 v162, v162, v95
	v_cvt_pk_bf16_f32 v87, v94, v95
	v_add_f32_e32 v131, v131, v182
	v_add_f32_e32 v130, v130, v162
	s_setprio 1
	s_waitcnt lgkmcnt(6)
	v_mfma_f32_32x32x16_bf16 v[64:79], v[248:251], v[96:99], v[64:79]
	v_mfma_f32_32x32x16_bf16 v[32:47], v[248:251], v[80:83], v[32:47]
	s_waitcnt lgkmcnt(4)
	v_mfma_f32_32x32x16_bf16 v[48:63], v[158:161], v[96:99], v[48:63]
	v_mfma_f32_32x32x16_bf16 v[16:31], v[158:161], v[80:83], v[16:31]
	ds_read_b128 v[248:251], v180 offset:6656
	ds_read_b128 v[158:161], v180 offset:6688
	s_waitcnt lgkmcnt(4)
	v_mfma_f32_32x32x16_bf16 v[64:79], v[104:107], v[100:103], v[64:79]
	s_waitcnt lgkmcnt(2)
	v_mfma_f32_32x32x16_bf16 v[48:63], v[108:111], v[100:103], v[48:63]
	v_mfma_f32_32x32x16_bf16 v[32:47], v[104:107], v[84:87], v[32:47]
	v_mfma_f32_32x32x16_bf16 v[16:31], v[108:111], v[84:87], v[16:31]
	s_setprio 1
	s_waitcnt lgkmcnt(1)
	v_mfma_f32_32x32x16_bf16 v[96:111], v[248:251], v[132:135], v[0:15]
	v_mfma_f32_32x32x16_bf16 v[80:95], v[248:251], v[214:217], v[0:15]
	ds_read_b128 v[248:251], v180 offset:6720
	s_waitcnt lgkmcnt(1)
; #define LAS __attribute__((address_space(3)))
; __device__ __forceinline__ unsigned pk2(float lo, float hi) { f32x2_t v = {lo, hi}; bf16x2_t b = __builtin_convertvector(v, bf16x2_t); return __builtin_bit_cast(unsigned, b); }
; #define MFMA32(a, b, c) __builtin_amdgcn_mfma_f32_32x32x16_bf16((a), (b), (c), 0, 0, 0)
; __device__ __forceinline__ void attn_unit64(const bf16_t* Q, const bf16_t* K, const bf16_t* Vt, bf16_t* O, int bh, int qb8, float mfix, LAS unsigned char* lds) {
;     ...
;                 for (int d0 = 0; d0 < 6; ++d0) { const bf16x8 a = *(const LAS bf16x8*)(kp + half * 32 * 104 + 16 * d0); const bf16x8 qa_ = Qs[512 * d0], qb_ = Qs[512 * (6 + d0)]; sA = MFMA32(a, qa_, sA); sB = MFMA32(a, qb_, sB); }
;                 if (t == tmaxw) {
;                     const int rowA = qw + r, rowB = qw + 32 + r;
; #pragma unroll
;                     for (int i = 0; i < 16; ++i) { const int kv = 64 * t + 32 * half + crow(i, hh); if (kv > rowA) sA[i] = -1e30f; if (kv > rowB) sB[i] = -1e30f; }
;                 }
;                 float la = 0.f, lb_ = 0.f;
; #pragma unroll
;                 for (int i = 0; i < 16; ++i) { sA[i] = __builtin_amdgcn_exp2f(sA[i]); sB[i] = __builtin_amdgcn_exp2f(sB[i]); la += sA[i]; lb_ += sB[i]; }
;                 lA += la; lB += lb_;
;                 u32x4 pwA[2], pwB[2];
; #pragma unroll
;                 for (int e = 0; e < 4; ++e) { pwA[0][e] = pk2(sA[2 * e], sA[2 * e + 1]); pwA[1][e] = pk2(sA[8 + 2 * e], sA[8 + 2 * e + 1]); pwB[0][e] = pk2(sB[2 * e], sB[2 * e + 1]); pwB[1][e] = pk2(sB[8 + 2 * e], sB[8 + 2 * e + 1]); }
; #pragma unroll
;                 for (int k2 = 0; k2 < 2; ++k2) { const int ks = 2 * half + k2;
;                     const u32x2 va0 = *(const LAS u32x2*)(vp + 16 * ks), va1 = *(const LAS u32x2*)(vp + 16 * ks + 8), vb0 = *(const LAS u32x2*)(vp + 32 * 68 + 16 * ks), vb1 = *(const LAS u32x2*)(vp + 32 * 68 + 16 * ks + 8);
;                     const bf16x8 v0 = __builtin_bit_cast(bf16x8, (u32x4){va0[0], va0[1], va1[0], va1[1]}), v1 = __builtin_bit_cast(bf16x8, (u32x4){vb0[0], vb0[1], vb1[0], vb1[1]});
;                     const bf16x8 pfA = __builtin_bit_cast(bf16x8, pwA[k2]), pfB = __builtin_bit_cast(bf16x8, pwB[k2]);
;                     oA0 = MFMA32(v0, pfA, oA0); oA1 = MFMA32(v1, pfA, oA1); oB0 = MFMA32(v0, pfB, oB0); oB1 = MFMA32(v1, pfB, oB1); }
	v_mfma_f32_32x32x16_bf16 v[96:111], v[158:161], v[136:139], v[96:111]
	v_mfma_f32_32x32x16_bf16 v[80:95], v[158:161], v[218:221], v[80:95]
	ds_read_b128 v[158:161], v180 offset:6752
	s_waitcnt lgkmcnt(1)
	v_mfma_f32_32x32x16_bf16 v[96:111], v[248:251], v[140:143], v[96:111]
	v_mfma_f32_32x32x16_bf16 v[80:95], v[248:251], v[232:235], v[80:95]
	ds_read_b128 v[248:251], v180 offset:6784
	s_waitcnt lgkmcnt(1)
	v_mfma_f32_32x32x16_bf16 v[96:111], v[158:161], v[144:147], v[96:111]
	v_mfma_f32_32x32x16_bf16 v[80:95], v[158:161], v[236:239], v[80:95]
	ds_read_b128 v[158:161], v180 offset:6816
	s_waitcnt lgkmcnt(1)
	v_mfma_f32_32x32x16_bf16 v[96:111], v[248:251], v[206:209], v[96:111]
	v_mfma_f32_32x32x16_bf16 v[80:95], v[248:251], v[240:243], v[80:95]
	s_waitcnt lgkmcnt(0)
	v_mfma_f32_32x32x16_bf16 v[96:111], v[158:161], v[210:213], v[96:111]
	v_mfma_f32_32x32x16_bf16 v[80:95], v[158:161], v[244:247], v[80:95]
	ds_read_b64 v[248:249], v178 offset:64
	ds_read_b64 v[250:251], v178 offset:80
	ds_read_b64 v[158:159], v178 offset:4416
	ds_read_b64 v[160:161], v178 offset:4432
	s_setprio 0
	s_nop 5
	v_exp_f32_e32 v96, v96
	v_exp_f32_e32 v97, v97
	v_exp_f32_e32 v98, v98
	v_exp_f32_e32 v99, v99
	v_add_f32_e32 v182, v96, v97
	v_cvt_pk_bf16_f32 v96, v96, v97
	v_exp_f32_e32 v100, v100
	v_exp_f32_e32 v101, v101
	v_add_f32_e32 v182, v182, v98
	v_add_f32_e32 v182, v182, v99
	v_cvt_pk_bf16_f32 v97, v98, v99
	v_exp_f32_e32 v102, v102
	v_exp_f32_e32 v103, v103
	v_add_f32_e32 v182, v182, v100
	v_add_f32_e32 v182, v182, v101
	v_cvt_pk_bf16_f32 v98, v100, v101
	v_exp_f32_e32 v80, v80
	v_exp_f32_e32 v81, v81
	v_add_f32_e32 v182, v182, v102
	v_add_f32_e32 v182, v182, v103
	v_cvt_pk_bf16_f32 v99, v102, v103
	v_exp_f32_e32 v82, v82
	v_exp_f32_e32 v83, v83
	v_add_f32_e32 v162, v80, v81
	v_cvt_pk_bf16_f32 v80, v80, v81
	v_exp_f32_e32 v84, v84
	v_exp_f32_e32 v85, v85
	v_add_f32_e32 v162, v162, v82
	v_add_f32_e32 v162, v162, v83
	v_cvt_pk_bf16_f32 v81, v82, v83
	v_exp_f32_e32 v86, v86
	v_exp_f32_e32 v87, v87
	v_add_f32_e32 v162, v162, v84
	v_add_f32_e32 v162, v162, v85
	v_cvt_pk_bf16_f32 v82, v84, v85
	v_exp_f32_e32 v104, v104
	v_exp_f32_e32 v105, v105
	v_add_f32_e32 v162, v162, v86
	v_add_f32_e32 v162, v162, v87
	v_cvt_pk_bf16_f32 v83, v86, v87
	v_exp_f32_e32 v106, v106
	v_exp_f32_e32 v107, v107
	v_add_f32_e32 v182, v182, v104
	v_add_f32_e32 v182, v182, v105
	v_cvt_pk_bf16_f32 v100, v104, v105
	v_exp_f32_e32 v108, v108
	v_exp_f32_e32 v109, v109
	v_add_f32_e32 v182, v182, v106
	v_add_f32_e32 v182, v182, v107
	v_cvt_pk_bf16_f32 v101, v106, v107
	v_exp_f32_e32 v110, v110
	v_exp_f32_e32 v111, v111
	v_add_f32_e32 v182, v182, v108
	v_add_f32_e32 v182, v182, v109
	v_cvt_pk_bf16_f32 v102, v108, v109
	v_exp_f32_e32 v88, v88
	v_exp_f32_e32 v89, v89
	v_add_f32_e32 v182, v182, v110
	v_add_f32_e32 v182, v182, v111
	v_cvt_pk_bf16_f32 v103, v110, v111
	ds_read_b64 v[104:105], v178 offset:96
	ds_read_b64 v[106:107], v178 offset:112
	ds_read_b64 v[108:109], v178 offset:4448
	ds_read_b64 v[110:111], v178 offset:4464
	v_exp_f32_e32 v90, v90
	v_exp_f32_e32 v91, v91
	v_add_f32_e32 v162, v162, v88
	v_add_f32_e32 v162, v162, v89
	v_cvt_pk_bf16_f32 v84, v88, v89
	v_exp_f32_e32 v92, v92
	v_exp_f32_e32 v93, v93
	v_add_f32_e32 v162, v162, v90
	v_add_f32_e32 v162, v162, v91
	v_cvt_pk_bf16_f32 v85, v90, v91
	v_exp_f32_e32 v94, v94
	v_exp_f32_e32 v95, v95
	v_add_f32_e32 v162, v162, v92
	v_add_f32_e32 v162, v162, v93
	v_cvt_pk_bf16_f32 v86, v92, v93
	v_add_f32_e32 v162, v162, v94
	v_add_f32_e32 v162, v162, v95
	v_cvt_pk_bf16_f32 v87, v94, v95
	v_add_f32_e32 v131, v131, v182
	v_add_f32_e32 v130, v130, v162
	s_setprio 1
	s_waitcnt lgkmcnt(6)
	v_mfma_f32_32x32x16_bf16 v[64:79], v[248:251], v[96:99], v[64:79]
	v_mfma_f32_32x32x16_bf16 v[32:47], v[248:251], v[80:83], v[32:47]
	s_waitcnt lgkmcnt(4)
	v_mfma_f32_32x32x16_bf16 v[48:63], v[158:161], v[96:99], v[48:63]
	v_mfma_f32_32x32x16_bf16 v[16:31], v[158:161], v[80:83], v[16:31]
	s_waitcnt lgkmcnt(2)
	v_mfma_f32_32x32x16_bf16 v[64:79], v[104:107], v[100:103], v[64:79]
	s_waitcnt lgkmcnt(0)
	v_mfma_f32_32x32x16_bf16 v[48:63], v[108:111], v[100:103], v[48:63]
	v_mfma_f32_32x32x16_bf16 v[32:47], v[104:107], v[84:87], v[32:47]
	v_mfma_f32_32x32x16_bf16 v[16:31], v[108:111], v[84:87], v[16:31]
	s_setprio 0
	s_branch .Lattn_join_2
.Lattn_fastd_2:
	s_mul_i32 s4, s29, 0x3400
	v_add_u32_e32 v180, s4, v188
	s_mul_i32 s4, s29, 0x2200
	v_add_u32_e32 v177, s4, v198
	v_add_u32_e32 v178, 0x6800, v177
	ds_read_b128 v[248:251], v180
	ds_read_b128 v[158:161], v180 offset:32
	s_cmp_lg_u64 s[20:21], 0
	s_cbranch_scc0 .Lattn_nold_2d
	global_load_dwordx4 v[112:115], v[124:125], off
	s_and_saveexec_b64 s[4:5], s[0:1]
	v_add_co_u32_e32 v252, vcc, 0x2000, v124
	s_nop 1
	v_addc_co_u32_e32 v253, vcc, 0, v125, vcc
	global_load_dwordx4 v[116:119], v[252:253], off
	s_or_b64 exec, exec, s[4:5]
	global_load_dwordx4 v[120:123], v[126:127], off
; #define LAS __attribute__((address_space(3)))
; __device__ __forceinline__ unsigned pk2(float lo, float hi) { f32x2_t v = {lo, hi}; bf16x2_t b = __builtin_convertvector(v, bf16x2_t); return __builtin_bit_cast(unsigned, b); }
; #define MFMA32(a, b, c) __builtin_amdgcn_mfma_f32_32x32x16_bf16((a), (b), (c), 0, 0, 0)
; __device__ __forceinline__ int crow(int r, int hi) { return (r & 3) + 8 * (r >> 2) + 4 * hi; }
; __device__ __forceinline__ void attn_unit64(const bf16_t* Q, const bf16_t* K, const bf16_t* Vt, bf16_t* O, int bh, int qb8, float mfix, LAS unsigned char* lds) {
;     ...
;                 for (int d0 = 0; d0 < 6; ++d0) { const bf16x8 a = *(const LAS bf16x8*)(kp + half * 32 * 104 + 16 * d0); const bf16x8 qa_ = Qs[512 * d0], qb_ = Qs[512 * (6 + d0)]; sA = MFMA32(a, qa_, sA); sB = MFMA32(a, qb_, sB); }
;                 if (t == tmaxw) {
;                     const int rowA = qw + r, rowB = qw + 32 + r;
; #pragma unroll
;                     for (int i = 0; i < 16; ++i) { const int kv = 64 * t + 32 * half + crow(i, hh); if (kv > rowA) sA[i] = -1e30f; if (kv > rowB) sB[i] = -1e30f; }
;                 }
;                 float la = 0.f, lb_ = 0.f;
; #pragma unroll
;                 for (int i = 0; i < 16; ++i) { sA[i] = __builtin_amdgcn_exp2f(sA[i]); sB[i] = __builtin_amdgcn_exp2f(sB[i]); la += sA[i]; lb_ += sB[i]; }
;                 lA += la; lB += lb_;
;                 u32x4 pwA[2], pwB[2];
; #pragma unroll
;                 for (int e = 0; e < 4; ++e) { pwA[0][e] = pk2(sA[2 * e], sA[2 * e + 1]); pwA[1][e] = pk2(sA[8 + 2 * e], sA[8 + 2 * e + 1]); pwB[0][e] = pk2(sB[2 * e], sB[2 * e + 1]); pwB[1][e] = pk2(sB[8 + 2 * e], sB[8 + 2 * e + 1]); }
.Lattn_nold_2d:
	s_nop 3
	s_setprio 1
	s_waitcnt lgkmcnt(1)
	v_mfma_f32_32x32x16_bf16 v[96:111], v[248:251], v[132:135], v[0:15]
	v_mfma_f32_32x32x16_bf16 v[80:95], v[248:251], v[214:217], v[0:15]
	ds_read_b128 v[248:251], v180 offset:64
	s_waitcnt lgkmcnt(1)
	v_mfma_f32_32x32x16_bf16 v[96:111], v[158:161], v[136:139], v[96:111]
	v_mfma_f32_32x32x16_bf16 v[80:95], v[158:161], v[218:221], v[80:95]
	ds_read_b128 v[158:161], v180 offset:96
	s_waitcnt lgkmcnt(1)
	v_mfma_f32_32x32x16_bf16 v[96:111], v[248:251], v[140:143], v[96:111]
	v_mfma_f32_32x32x16_bf16 v[80:95], v[248:251], v[232:235], v[80:95]
	ds_read_b128 v[248:251], v180 offset:128
	s_waitcnt lgkmcnt(1)
	v_mfma_f32_32x32x16_bf16 v[96:111], v[158:161], v[144:147], v[96:111]
	v_mfma_f32_32x32x16_bf16 v[80:95], v[158:161], v[236:239], v[80:95]
	ds_read_b128 v[158:161], v180 offset:160
	s_waitcnt lgkmcnt(1)
	v_mfma_f32_32x32x16_bf16 v[96:111], v[248:251], v[206:209], v[96:111]
	v_mfma_f32_32x32x16_bf16 v[80:95], v[248:251], v[240:243], v[80:95]
	s_waitcnt lgkmcnt(0)
	v_mfma_f32_32x32x16_bf16 v[96:111], v[158:161], v[210:213], v[96:111]
	v_mfma_f32_32x32x16_bf16 v[80:95], v[158:161], v[244:247], v[80:95]
	v_add_u32_e32 v167, s27, v194
	v_sub_u32_e32 v172, v165, v167
	v_sub_u32_e32 v173, v166, v167
	v_cmp_gt_i32_e32 vcc, 0, v172
	v_cmp_gt_i32_e64 s[4:5], 1, v172
	v_cmp_gt_i32_e64 s[100:101], 2, v172
	s_nop 4
	v_cndmask_b32_e64 v96, v96, v129, vcc
	v_cmp_gt_i32_e32 vcc, 3, v172
	v_cndmask_b32_e64 v97, v97, v129, s[4:5]
	v_cmp_gt_i32_e64 s[4:5], 8, v172
	v_cndmask_b32_e64 v98, v98, v129, s[100:101]
	v_cmp_gt_i32_e64 s[100:101], 9, v172
	v_cndmask_b32_e64 v99, v99, v129, vcc
	v_cmp_gt_i32_e32 vcc, 10, v172
	v_cndmask_b32_e64 v100, v100, v129, s[4:5]
	v_cmp_gt_i32_e64 s[4:5], 11, v172
	v_cndmask_b32_e64 v101, v101, v129, s[100:101]
	v_cmp_gt_i32_e64 s[100:101], 16, v172
	v_cndmask_b32_e64 v102, v102, v129, vcc
	v_cmp_gt_i32_e32 vcc, 17, v172
	v_cndmask_b32_e64 v103, v103, v129, s[4:5]
	v_cmp_gt_i32_e64 s[4:5], 18, v172
	v_cndmask_b32_e64 v104, v104, v129, s[100:101]
	v_cmp_gt_i32_e64 s[100:101], 19, v172
	v_cndmask_b32_e64 v105, v105, v129, vcc
	v_cmp_gt_i32_e32 vcc, 24, v172
	v_cndmask_b32_e64 v106, v106, v129, s[4:5]
	v_cmp_gt_i32_e64 s[4:5], 25, v172
	v_cndmask_b32_e64 v107, v107, v129, s[100:101]
	v_cmp_gt_i32_e64 s[100:101], 26, v172
	v_cndmask_b32_e64 v108, v108, v129, vcc
	v_cmp_gt_i32_e32 vcc, 27, v172
	v_cndmask_b32_e64 v109, v109, v129, s[4:5]
	v_cmp_gt_i32_e64 s[4:5], 0, v173
	v_cndmask_b32_e64 v110, v110, v129, s[100:101]
	v_cmp_gt_i32_e64 s[100:101], 1, v173
	v_cndmask_b32_e64 v111, v111, v129, vcc
	v_cmp_gt_i32_e32 vcc, 2, v173
	v_cndmask_b32_e64 v80, v80, v129, s[4:5]
	v_cmp_gt_i32_e64 s[4:5], 3, v173
	v_cndmask_b32_e64 v81, v81, v129, s[100:101]
	v_cmp_gt_i32_e64 s[100:101], 8, v173
	v_cndmask_b32_e64 v82, v82, v129, vcc
	v_cmp_gt_i32_e32 vcc, 9, v173
	v_cndmask_b32_e64 v83, v83, v129, s[4:5]
	v_cmp_gt_i32_e64 s[4:5], 10, v173
	v_cndmask_b32_e64 v84, v84, v129, s[100:101]
	v_cmp_gt_i32_e64 s[100:101], 11, v173
	v_cndmask_b32_e64 v85, v85, v129, vcc
	v_cmp_gt_i32_e32 vcc, 16, v173
	v_cndmask_b32_e64 v86, v86, v129, s[4:5]
	v_cmp_gt_i32_e64 s[4:5], 17, v173
	v_cndmask_b32_e64 v87, v87, v129, s[100:101]
	v_cmp_gt_i32_e64 s[100:101], 18, v173
	v_cndmask_b32_e64 v88, v88, v129, vcc
	v_cmp_gt_i32_e32 vcc, 19, v173
	v_cndmask_b32_e64 v89, v89, v129, s[4:5]
	v_cmp_gt_i32_e64 s[4:5], 24, v173
	v_cndmask_b32_e64 v90, v90, v129, s[100:101]
	v_cmp_gt_i32_e64 s[100:101], 25, v173
	v_cndmask_b32_e64 v91, v91, v129, vcc
	v_cmp_gt_i32_e32 vcc, 26, v173
	v_cndmask_b32_e64 v92, v92, v129, s[4:5]
	v_cmp_gt_i32_e64 s[4:5], 27, v173
	v_cndmask_b32_e64 v93, v93, v129, s[100:101]
	v_cndmask_b32_e64 v94, v94, v129, vcc
	v_cndmask_b32_e64 v95, v95, v129, s[4:5]
	ds_read_b64 v[248:249], v178 offset:0
	ds_read_b64 v[250:251], v178 offset:16
	ds_read_b64 v[158:159], v178 offset:4352
	ds_read_b64 v[160:161], v178 offset:4368
	s_setprio 0
	v_exp_f32_e32 v96, v96
	v_exp_f32_e32 v97, v97
	v_exp_f32_e32 v98, v98
	v_exp_f32_e32 v99, v99
	v_add_f32_e32 v182, v96, v97
	v_cvt_pk_bf16_f32 v96, v96, v97
	v_exp_f32_e32 v100, v100
	v_exp_f32_e32 v101, v101
	v_add_f32_e32 v182, v182, v98
	v_add_f32_e32 v182, v182, v99
	v_cvt_pk_bf16_f32 v97, v98, v99
	v_exp_f32_e32 v102, v102
	v_exp_f32_e32 v103, v103
	v_add_f32_e32 v182, v182, v100
	v_add_f32_e32 v182, v182, v101
	v_cvt_pk_bf16_f32 v98, v100, v101
	v_exp_f32_e32 v80, v80
	v_exp_f32_e32 v81, v81
	v_add_f32_e32 v182, v182, v102
	v_add_f32_e32 v182, v182, v103
	v_cvt_pk_bf16_f32 v99, v102, v103
	v_exp_f32_e32 v82, v82
	v_exp_f32_e32 v83, v83
	v_add_f32_e32 v162, v80, v81
	v_cvt_pk_bf16_f32 v80, v80, v81
	v_exp_f32_e32 v84, v84
	v_exp_f32_e32 v85, v85
	v_add_f32_e32 v162, v162, v82
	v_add_f32_e32 v162, v162, v83
	v_cvt_pk_bf16_f32 v81, v82, v83
	v_exp_f32_e32 v86, v86
	v_exp_f32_e32 v87, v87
	v_add_f32_e32 v162, v162, v84
	v_add_f32_e32 v162, v162, v85
	v_cvt_pk_bf16_f32 v82, v84, v85
	v_exp_f32_e32 v104, v104
	v_exp_f32_e32 v105, v105
	v_add_f32_e32 v162, v162, v86
	v_add_f32_e32 v162, v162, v87
	v_cvt_pk_bf16_f32 v83, v86, v87
	v_exp_f32_e32 v106, v106
	v_exp_f32_e32 v107, v107
	v_add_f32_e32 v182, v182, v104
	v_add_f32_e32 v182, v182, v105
	v_cvt_pk_bf16_f32 v100, v104, v105
	v_exp_f32_e32 v108, v108
	v_exp_f32_e32 v109, v109
	v_add_f32_e32 v182, v182, v106
	v_add_f32_e32 v182, v182, v107
	v_cvt_pk_bf16_f32 v101, v106, v107
	v_exp_f32_e32 v110, v110
	v_exp_f32_e32 v111, v111
	v_add_f32_e32 v182, v182, v108
	v_add_f32_e32 v182, v182, v109
	v_cvt_pk_bf16_f32 v102, v108, v109
	v_exp_f32_e32 v88, v88
	v_exp_f32_e32 v89, v89
	v_add_f32_e32 v182, v182, v110
	v_add_f32_e32 v182, v182, v111
	v_cvt_pk_bf16_f32 v103, v110, v111
	ds_read_b64 v[104:105], v178 offset:32
	ds_read_b64 v[106:107], v178 offset:48
	ds_read_b64 v[108:109], v178 offset:4384
	ds_read_b64 v[110:111], v178 offset:4400
	v_exp_f32_e32 v90, v90
	v_exp_f32_e32 v91, v91
	v_add_f32_e32 v162, v162, v88
	v_add_f32_e32 v162, v162, v89
	v_cvt_pk_bf16_f32 v84, v88, v89
	v_exp_f32_e32 v92, v92
	v_exp_f32_e32 v93, v93
	v_add_f32_e32 v162, v162, v90
	v_add_f32_e32 v162, v162, v91
	v_cvt_pk_bf16_f32 v85, v90, v91
	v_exp_f32_e32 v94, v94
	v_exp_f32_e32 v95, v95
	v_add_f32_e32 v162, v162, v92
	v_add_f32_e32 v162, v162, v93
	v_cvt_pk_bf16_f32 v86, v92, v93
	v_add_f32_e32 v162, v162, v94
	v_add_f32_e32 v162, v162, v95
	v_cvt_pk_bf16_f32 v87, v94, v95
	v_add_f32_e32 v131, v131, v182
	v_add_f32_e32 v130, v130, v162
	s_setprio 1
	s_waitcnt lgkmcnt(6)
; #define LAS __attribute__((address_space(3)))
; __device__ __forceinline__ unsigned pk2(float lo, float hi) { f32x2_t v = {lo, hi}; bf16x2_t b = __builtin_convertvector(v, bf16x2_t); return __builtin_bit_cast(unsigned, b); }
; #define MFMA32(a, b, c) __builtin_amdgcn_mfma_f32_32x32x16_bf16((a), (b), (c), 0, 0, 0)
; __device__ __forceinline__ void attn_unit64(const bf16_t* Q, const bf16_t* K, const bf16_t* Vt, bf16_t* O, int bh, int qb8, float mfix, LAS unsigned char* lds) {
;     ...
;                 for (int d0 = 0; d0 < 6; ++d0) { const bf16x8 a = *(const LAS bf16x8*)(kp + half * 32 * 104 + 16 * d0); const bf16x8 qa_ = Qs[512 * d0], qb_ = Qs[512 * (6 + d0)]; sA = MFMA32(a, qa_, sA); sB = MFMA32(a, qb_, sB); }
;     ...
;                 for (int e = 0; e < 4; ++e) { pwA[0][e] = pk2(sA[2 * e], sA[2 * e + 1]); pwA[1][e] = pk2(sA[8 + 2 * e], sA[8 + 2 * e + 1]); pwB[0][e] = pk2(sB[2 * e], sB[2 * e + 1]); pwB[1][e] = pk2(sB[8 + 2 * e], sB[8 + 2 * e + 1]); }
; #pragma unroll
;                 for (int k2 = 0; k2 < 2; ++k2) { const int ks = 2 * half + k2;
;                     const u32x2 va0 = *(const LAS u32x2*)(vp + 16 * ks), va1 = *(const LAS u32x2*)(vp + 16 * ks + 8), vb0 = *(const LAS u32x2*)(vp + 32 * 68 + 16 * ks), vb1 = *(const LAS u32x2*)(vp + 32 * 68 + 16 * ks + 8);
;                     const bf16x8 v0 = __builtin_bit_cast(bf16x8, (u32x4){va0[0], va0[1], va1[0], va1[1]}), v1 = __builtin_bit_cast(bf16x8, (u32x4){vb0[0], vb0[1], vb1[0], vb1[1]});
;                     const bf16x8 pfA = __builtin_bit_cast(bf16x8, pwA[k2]), pfB = __builtin_bit_cast(bf16x8, pwB[k2]);
;                     oA0 = MFMA32(v0, pfA, oA0); oA1 = MFMA32(v1, pfA, oA1); oB0 = MFMA32(v0, pfB, oB0); oB1 = MFMA32(v1, pfB, oB1); }
	v_mfma_f32_32x32x16_bf16 v[64:79], v[248:251], v[96:99], v[64:79]
	v_mfma_f32_32x32x16_bf16 v[32:47], v[248:251], v[80:83], v[32:47]
	s_waitcnt lgkmcnt(4)
	v_mfma_f32_32x32x16_bf16 v[48:63], v[158:161], v[96:99], v[48:63]
	v_mfma_f32_32x32x16_bf16 v[16:31], v[158:161], v[80:83], v[16:31]
	ds_read_b128 v[248:251], v180 offset:6656
	ds_read_b128 v[158:161], v180 offset:6688
	s_waitcnt lgkmcnt(4)
	v_mfma_f32_32x32x16_bf16 v[64:79], v[104:107], v[100:103], v[64:79]
	s_waitcnt lgkmcnt(2)
	v_mfma_f32_32x32x16_bf16 v[48:63], v[108:111], v[100:103], v[48:63]
	v_mfma_f32_32x32x16_bf16 v[32:47], v[104:107], v[84:87], v[32:47]
	v_mfma_f32_32x32x16_bf16 v[16:31], v[108:111], v[84:87], v[16:31]
	s_setprio 1
	s_waitcnt lgkmcnt(1)
	v_mfma_f32_32x32x16_bf16 v[96:111], v[248:251], v[132:135], v[0:15]
	v_mfma_f32_32x32x16_bf16 v[80:95], v[248:251], v[214:217], v[0:15]
	ds_read_b128 v[248:251], v180 offset:6720
	s_waitcnt lgkmcnt(1)
	v_mfma_f32_32x32x16_bf16 v[96:111], v[158:161], v[136:139], v[96:111]
	v_mfma_f32_32x32x16_bf16 v[80:95], v[158:161], v[218:221], v[80:95]
	ds_read_b128 v[158:161], v180 offset:6752
	s_waitcnt lgkmcnt(1)
	v_mfma_f32_32x32x16_bf16 v[96:111], v[248:251], v[140:143], v[96:111]
	v_mfma_f32_32x32x16_bf16 v[80:95], v[248:251], v[232:235], v[80:95]
	ds_read_b128 v[248:251], v180 offset:6784
	s_waitcnt lgkmcnt(1)
	v_mfma_f32_32x32x16_bf16 v[96:111], v[158:161], v[144:147], v[96:111]
	v_mfma_f32_32x32x16_bf16 v[80:95], v[158:161], v[236:239], v[80:95]
	ds_read_b128 v[158:161], v180 offset:6816
	s_waitcnt lgkmcnt(1)
	v_mfma_f32_32x32x16_bf16 v[96:111], v[248:251], v[206:209], v[96:111]
	v_mfma_f32_32x32x16_bf16 v[80:95], v[248:251], v[240:243], v[80:95]
	s_waitcnt lgkmcnt(0)
; #define LAS __attribute__((address_space(3)))
; __device__ __forceinline__ unsigned pk2(float lo, float hi) { f32x2_t v = {lo, hi}; bf16x2_t b = __builtin_convertvector(v, bf16x2_t); return __builtin_bit_cast(unsigned, b); }
; #define MFMA32(a, b, c) __builtin_amdgcn_mfma_f32_32x32x16_bf16((a), (b), (c), 0, 0, 0)
; __device__ __forceinline__ void attn_unit64(const bf16_t* Q, const bf16_t* K, const bf16_t* Vt, bf16_t* O, int bh, int qb8, float mfix, LAS unsigned char* lds) {
;     ...
;                 for (int d0 = 0; d0 < 6; ++d0) { const bf16x8 a = *(const LAS bf16x8*)(kp + half * 32 * 104 + 16 * d0); const bf16x8 qa_ = Qs[512 * d0], qb_ = Qs[512 * (6 + d0)]; sA = MFMA32(a, qa_, sA); sB = MFMA32(a, qb_, sB); }
;                 if (t == tmaxw) {
;                     const int rowA = qw + r, rowB = qw + 32 + r;
; #pragma unroll
;                     for (int i = 0; i < 16; ++i) { const int kv = 64 * t + 32 * half + crow(i, hh); if (kv > rowA) sA[i] = -1e30f; if (kv > rowB) sB[i] = -1e30f; }
;                 }
;                 float la = 0.f, lb_ = 0.f;
; #pragma unroll
;                 for (int i = 0; i < 16; ++i) { sA[i] = __builtin_amdgcn_exp2f(sA[i]); sB[i] = __builtin_amdgcn_exp2f(sB[i]); la += sA[i]; lb_ += sB[i]; }
;                 lA += la; lB += lb_;
;                 u32x4 pwA[2], pwB[2];
; #pragma unroll
;                 for (int e = 0; e < 4; ++e) { pwA[0][e] = pk2(sA[2 * e], sA[2 * e + 1]); pwA[1][e] = pk2(sA[8 + 2 * e], sA[8 + 2 * e + 1]); pwB[0][e] = pk2(sB[2 * e], sB[2 * e + 1]); pwB[1][e] = pk2(sB[8 + 2 * e], sB[8 + 2 * e + 1]); }
; #pragma unroll
;                 for (int k2 = 0; k2 < 2; ++k2) { const int ks = 2 * half + k2;
;                     const u32x2 va0 = *(const LAS u32x2*)(vp + 16 * ks), va1 = *(const LAS u32x2*)(vp + 16 * ks + 8), vb0 = *(const LAS u32x2*)(vp + 32 * 68 + 16 * ks), vb1 = *(const LAS u32x2*)(vp + 32 * 68 + 16 * ks + 8);
;                     const bf16x8 v0 = __builtin_bit_cast(bf16x8, (u32x4){va0[0], va0[1], va1[0], va1[1]}), v1 = __builtin_bit_cast(bf16x8, (u32x4){vb0[0], vb0[1], vb1[0], vb1[1]});
;                     const bf16x8 pfA = __builtin_bit_cast(bf16x8, pwA[k2]), pfB = __builtin_bit_cast(bf16x8, pwB[k2]);
;                     oA0 = MFMA32(v0, pfA, oA0); oA1 = MFMA32(v1, pfA, oA1); oB0 = MFMA32(v0, pfB, oB0); oB1 = MFMA32(v1, pfB, oB1); }
	v_mfma_f32_32x32x16_bf16 v[96:111], v[158:161], v[210:213], v[96:111]
	v_mfma_f32_32x32x16_bf16 v[80:95], v[158:161], v[244:247], v[80:95]
	v_cmp_gt_i32_e32 vcc, 32, v172
	v_cmp_gt_i32_e64 s[4:5], 33, v172
	v_cmp_gt_i32_e64 s[100:101], 34, v172
	s_nop 7
	v_cndmask_b32_e64 v96, v96, v129, vcc
	v_cmp_gt_i32_e32 vcc, 35, v172
	v_cndmask_b32_e64 v97, v97, v129, s[4:5]
	v_cmp_gt_i32_e64 s[4:5], 40, v172
	v_cndmask_b32_e64 v98, v98, v129, s[100:101]
	v_cmp_gt_i32_e64 s[100:101], 41, v172
	v_cndmask_b32_e64 v99, v99, v129, vcc
	v_cmp_gt_i32_e32 vcc, 42, v172
	v_cndmask_b32_e64 v100, v100, v129, s[4:5]
	v_cmp_gt_i32_e64 s[4:5], 43, v172
	v_cndmask_b32_e64 v101, v101, v129, s[100:101]
	v_cmp_gt_i32_e64 s[100:101], 48, v172
	v_cndmask_b32_e64 v102, v102, v129, vcc
	v_cmp_gt_i32_e32 vcc, 49, v172
	v_cndmask_b32_e64 v103, v103, v129, s[4:5]
	v_cmp_gt_i32_e64 s[4:5], 50, v172
	v_cndmask_b32_e64 v104, v104, v129, s[100:101]
	v_cmp_gt_i32_e64 s[100:101], 51, v172
	v_cndmask_b32_e64 v105, v105, v129, vcc
	v_cmp_gt_i32_e32 vcc, 56, v172
	v_cndmask_b32_e64 v106, v106, v129, s[4:5]
	v_cmp_gt_i32_e64 s[4:5], 57, v172
	v_cndmask_b32_e64 v107, v107, v129, s[100:101]
	v_cmp_gt_i32_e64 s[100:101], 58, v172
	v_cndmask_b32_e64 v108, v108, v129, vcc
	v_cmp_gt_i32_e32 vcc, 59, v172
	v_cndmask_b32_e64 v109, v109, v129, s[4:5]
	v_cmp_gt_i32_e64 s[4:5], 32, v173
	v_cndmask_b32_e64 v110, v110, v129, s[100:101]
	v_cmp_gt_i32_e64 s[100:101], 33, v173
	v_cndmask_b32_e64 v111, v111, v129, vcc
	v_cmp_gt_i32_e32 vcc, 34, v173
	v_cndmask_b32_e64 v80, v80, v129, s[4:5]
	v_cmp_gt_i32_e64 s[4:5], 35, v173
	v_cndmask_b32_e64 v81, v81, v129, s[100:101]
	v_cmp_gt_i32_e64 s[100:101], 40, v173
	v_cndmask_b32_e64 v82, v82, v129, vcc
	v_cmp_gt_i32_e32 vcc, 41, v173
	v_cndmask_b32_e64 v83, v83, v129, s[4:5]
	v_cmp_gt_i32_e64 s[4:5], 42, v173
	v_cndmask_b32_e64 v84, v84, v129, s[100:101]
	v_cmp_gt_i32_e64 s[100:101], 43, v173
	v_cndmask_b32_e64 v85, v85, v129, vcc
	v_cmp_gt_i32_e32 vcc, 48, v173
	v_cndmask_b32_e64 v86, v86, v129, s[4:5]
	v_cmp_gt_i32_e64 s[4:5], 49, v173
	v_cndmask_b32_e64 v87, v87, v129, s[100:101]
	v_cmp_gt_i32_e64 s[100:101], 50, v173
	v_cndmask_b32_e64 v88, v88, v129, vcc
	v_cmp_gt_i32_e32 vcc, 51, v173
	v_cndmask_b32_e64 v89, v89, v129, s[4:5]
	v_cmp_gt_i32_e64 s[4:5], 56, v173
	v_cndmask_b32_e64 v90, v90, v129, s[100:101]
	v_cmp_gt_i32_e64 s[100:101], 57, v173
	v_cndmask_b32_e64 v91, v91, v129, vcc
	v_cmp_gt_i32_e32 vcc, 58, v173
	v_cndmask_b32_e64 v92, v92, v129, s[4:5]
	v_cmp_gt_i32_e64 s[4:5], 59, v173
	v_cndmask_b32_e64 v93, v93, v129, s[100:101]
	v_cndmask_b32_e64 v94, v94, v129, vcc
	v_cndmask_b32_e64 v95, v95, v129, s[4:5]
	ds_read_b64 v[248:249], v178 offset:64
	ds_read_b64 v[250:251], v178 offset:80
	ds_read_b64 v[158:159], v178 offset:4416
	ds_read_b64 v[160:161], v178 offset:4432
	s_setprio 0
	v_exp_f32_e32 v96, v96
	v_exp_f32_e32 v97, v97
	v_exp_f32_e32 v98, v98
	v_exp_f32_e32 v99, v99
	v_add_f32_e32 v182, v96, v97
	v_cvt_pk_bf16_f32 v96, v96, v97
	v_exp_f32_e32 v100, v100
	v_exp_f32_e32 v101, v101
	v_add_f32_e32 v182, v182, v98
	v_add_f32_e32 v182, v182, v99
	v_cvt_pk_bf16_f32 v97, v98, v99
	v_exp_f32_e32 v102, v102
	v_exp_f32_e32 v103, v103
	v_add_f32_e32 v182, v182, v100
	v_add_f32_e32 v182, v182, v101
	v_cvt_pk_bf16_f32 v98, v100, v101
	v_exp_f32_e32 v80, v80
	v_exp_f32_e32 v81, v81
	v_add_f32_e32 v182, v182, v102
	v_add_f32_e32 v182, v182, v103
	v_cvt_pk_bf16_f32 v99, v102, v103
	v_exp_f32_e32 v82, v82
	v_exp_f32_e32 v83, v83
	v_add_f32_e32 v162, v80, v81
	v_cvt_pk_bf16_f32 v80, v80, v81
	v_exp_f32_e32 v84, v84
	v_exp_f32_e32 v85, v85
	v_add_f32_e32 v162, v162, v82
	v_add_f32_e32 v162, v162, v83
	v_cvt_pk_bf16_f32 v81, v82, v83
	v_exp_f32_e32 v86, v86
	v_exp_f32_e32 v87, v87
	v_add_f32_e32 v162, v162, v84
	v_add_f32_e32 v162, v162, v85
	v_cvt_pk_bf16_f32 v82, v84, v85
	v_exp_f32_e32 v104, v104
	v_exp_f32_e32 v105, v105
	v_add_f32_e32 v162, v162, v86
	v_add_f32_e32 v162, v162, v87
	v_cvt_pk_bf16_f32 v83, v86, v87
	v_exp_f32_e32 v106, v106
	v_exp_f32_e32 v107, v107
	v_add_f32_e32 v182, v182, v104
	v_add_f32_e32 v182, v182, v105
	v_cvt_pk_bf16_f32 v100, v104, v105
	v_exp_f32_e32 v108, v108
	v_exp_f32_e32 v109, v109
	v_add_f32_e32 v182, v182, v106
	v_add_f32_e32 v182, v182, v107
	v_cvt_pk_bf16_f32 v101, v106, v107
	v_exp_f32_e32 v110, v110
	v_exp_f32_e32 v111, v111
	v_add_f32_e32 v182, v182, v108
	v_add_f32_e32 v182, v182, v109
	v_cvt_pk_bf16_f32 v102, v108, v109
	v_exp_f32_e32 v88, v88
	v_exp_f32_e32 v89, v89
	v_add_f32_e32 v182, v182, v110
	v_add_f32_e32 v182, v182, v111
	v_cvt_pk_bf16_f32 v103, v110, v111
	ds_read_b64 v[104:105], v178 offset:96
	ds_read_b64 v[106:107], v178 offset:112
	ds_read_b64 v[108:109], v178 offset:4448
	ds_read_b64 v[110:111], v178 offset:4464
	v_exp_f32_e32 v90, v90
	v_exp_f32_e32 v91, v91
	v_add_f32_e32 v162, v162, v88
	v_add_f32_e32 v162, v162, v89
	v_cvt_pk_bf16_f32 v84, v88, v89
	v_exp_f32_e32 v92, v92
	v_exp_f32_e32 v93, v93
	v_add_f32_e32 v162, v162, v90
	v_add_f32_e32 v162, v162, v91
	v_cvt_pk_bf16_f32 v85, v90, v91
	v_exp_f32_e32 v94, v94
	v_exp_f32_e32 v95, v95
	v_add_f32_e32 v162, v162, v92
	v_add_f32_e32 v162, v162, v93
	v_cvt_pk_bf16_f32 v86, v92, v93
	v_add_f32_e32 v162, v162, v94
	v_add_f32_e32 v162, v162, v95
	v_cvt_pk_bf16_f32 v87, v94, v95
	v_add_f32_e32 v131, v131, v182
	v_add_f32_e32 v130, v130, v162
	s_setprio 1
	s_waitcnt lgkmcnt(6)
	v_mfma_f32_32x32x16_bf16 v[64:79], v[248:251], v[96:99], v[64:79]
	v_mfma_f32_32x32x16_bf16 v[32:47], v[248:251], v[80:83], v[32:47]
	s_waitcnt lgkmcnt(4)
	v_mfma_f32_32x32x16_bf16 v[48:63], v[158:161], v[96:99], v[48:63]
	v_mfma_f32_32x32x16_bf16 v[16:31], v[158:161], v[80:83], v[16:31]
	s_waitcnt lgkmcnt(2)
	v_mfma_f32_32x32x16_bf16 v[64:79], v[104:107], v[100:103], v[64:79]
	s_waitcnt lgkmcnt(0)
	v_mfma_f32_32x32x16_bf16 v[48:63], v[108:111], v[100:103], v[48:63]
	v_mfma_f32_32x32x16_bf16 v[32:47], v[104:107], v[84:87], v[32:47]
	v_mfma_f32_32x32x16_bf16 v[16:31], v[108:111], v[84:87], v[16:31]
	s_setprio 0
	s_branch .Lattn_join_2
